# v28 + one static s_setprio 1 for waves 4-7 at kernel entry, all 96 per-segment s_setprio flips in the GEMM loops deleted
# baseline (speedup 1.0000x reference)
_Z4mega4Args:
	v_readfirstlane_b32 s98, v0
	s_nop 3
	s_and_b32 s98, s98, 0x3ff
	s_lshr_b32 s98, s98, 6
	s_cmp_ge_u32 s98, 4
	s_cbranch_scc0 .Lprio_done
	s_setprio 1
.Lprio_done:
	v_readfirstlane_b32 s8, v0
	v_writelane_b32 v248, s2, 0
	s_load_dwordx2 s[2:3], s[0:1], 0xc0
	s_load_dwordx4 s[4:7], s[0:1], 0xc8
	v_cmp_gt_u32_e32 vcc, 64, v0
	s_waitcnt lgkmcnt(0)
	v_writelane_b32 v248, s2, 1
	s_nop 1
	v_writelane_b32 v248, s3, 2
	s_load_dword s2, s[0:1], 0xd8
	v_writelane_b32 v248, s4, 3
	s_nop 1
	v_writelane_b32 v248, s5, 4
	v_writelane_b32 v248, s6, 5
	v_writelane_b32 v248, s7, 6
	s_waitcnt lgkmcnt(0)
	v_writelane_b32 v248, s2, 7
	s_add_u32 s2, s0, 0xd8
	s_addc_u32 s3, s1, 0
	v_writelane_b32 v248, s2, 8
	s_nop 1
	v_writelane_b32 v248, s3, 9
	s_and_saveexec_b64 s[2:3], vcc
	v_lshl_add_u32 v1, v0, 2, 0
	v_add_u32_e32 v1, 0x23f00, v1
	v_mov_b32_e32 v2, 0
	ds_write_b32 v1, v2
	s_or_b64 exec, exec, s[2:3]
	s_load_dwordx16 s[12:27], s[0:1], 0x0
	s_load_dwordx2 s[2:3], s[0:1], 0xc0
	s_load_dwordx4 s[4:7], s[0:1], 0xc8
	v_cmp_eq_u32_e32 vcc, 0, v0
	s_waitcnt lgkmcnt(0)
	v_writelane_b32 v248, s12, 10
	s_add_u32 s2, s2, 0x4000
	s_addc_u32 s3, s3, 0
	v_writelane_b32 v248, s13, 11
	v_writelane_b32 v248, s14, 12
	v_writelane_b32 v248, s15, 13
	v_writelane_b32 v248, s16, 14
	v_writelane_b32 v248, s17, 15
	v_writelane_b32 v248, s18, 16
	v_writelane_b32 v248, s19, 17
	v_writelane_b32 v248, s20, 18
	v_writelane_b32 v248, s21, 19
	v_writelane_b32 v248, s22, 20
	v_writelane_b32 v248, s23, 21
	v_writelane_b32 v248, s24, 22
	v_writelane_b32 v248, s25, 23
	v_writelane_b32 v248, s26, 24
	v_writelane_b32 v248, s27, 25
	s_load_dwordx16 s[12:27], s[0:1], 0x40
	s_cmp_eq_u32 s6, 0
	s_barrier
	s_waitcnt lgkmcnt(0)
	v_writelane_b32 v248, s12, 26
	s_nop 1
	v_writelane_b32 v248, s13, 27
	v_writelane_b32 v248, s14, 28
	v_writelane_b32 v248, s15, 29
	v_writelane_b32 v248, s16, 30
	v_writelane_b32 v248, s17, 31
	v_writelane_b32 v248, s18, 32
	v_writelane_b32 v248, s19, 33
	v_writelane_b32 v248, s20, 34
	v_writelane_b32 v248, s21, 35
	v_writelane_b32 v248, s22, 36
	v_writelane_b32 v248, s23, 37
	v_writelane_b32 v248, s24, 38
	v_writelane_b32 v248, s25, 39
	v_writelane_b32 v248, s26, 40
	v_writelane_b32 v248, s27, 41
	s_cbranch_scc1 .LBB0_7
	s_getreg_b32 s4, hwreg(HW_REG_XCC_ID, 0, 4)
	s_and_b32 s46, s4, 15
	s_and_saveexec_b64 s[4:5], vcc
	s_cbranch_execz .LBB0_6
	s_mov_b64 s[6:7], exec
	v_mbcnt_lo_u32_b32 v1, s6, 0
	v_mbcnt_hi_u32_b32 v1, s7, v1
	v_cmp_eq_u32_e32 vcc, 0, v1
	s_and_b64 s[10:11], exec, vcc
	s_mov_b64 exec, s[10:11]
	s_cbranch_execz .LBB0_6
	s_lshl_b32 s9, s46, 8
	s_bcnt1_i32_b64 s6, s[6:7]
	v_mov_b32_e32 v1, s9
	v_mov_b32_e32 v2, s6
	global_atomic_add v1, v2, s[2:3] offset:1024

.LBB0_104:
	s_add_u32 s10, s8, 0xfff00080
	s_addc_u32 s11, s9, -1
	s_add_i32 s34, 0, 0x10000
	s_cmp_eq_u32 s29, 60
	s_cselect_b32 s13, s7, s11
	s_cselect_b32 s12, s24, s10
	s_cselect_b32 s11, s25, s28
	s_cselect_b32 s10, s26, s27
	s_add_i32 s40, 0, 0x14000
	v_add_u32_e32 v158, s34, v162
	v_add_u32_e32 v172, s40, v162
	s_waitcnt lgkmcnt(0)
	ds_read_b128 v[132:135], v158
	ds_read_b128 v[136:139], v158 offset:1024
	ds_read_b128 v[154:157], v158 offset:2048
	ds_read_b128 v[158:161], v158 offset:3072
	ds_read_b128 v[184:187], v172
	ds_read_b128 v[188:191], v172 offset:1024
	ds_read_b128 v[192:195], v172 offset:2048
	ds_read_b128 v[196:199], v172 offset:3072
	v_lshl_add_u64 v[216:217], s[8:9], 0, v[150:151]
	s_add_i32 m0, s16, 0xc000
	ds_read_b128 v[200:203], v182
	ds_read_b128 v[204:207], v182 offset:1024
	ds_read_b128 v[208:211], v182 offset:2048
	ds_read_b128 v[212:215], v182 offset:3072
	ds_read_b128 v[232:235], v182 offset:4096
	ds_read_b128 v[236:239], v182 offset:5120
	ds_read_b128 v[240:243], v182 offset:6144
	ds_read_b128 v[244:247], v182 offset:7168
	global_load_lds_dwordx4 v[216:217], off
	v_lshl_add_u64 v[216:217], s[8:9], 0, v[152:153]
	s_add_i32 m0, s16, 0xe000
	s_nop 0
	global_load_lds_dwordx4 v[216:217], off
	s_waitcnt vmcnt(8)
	s_waitcnt lgkmcnt(0)
	s_barrier
	s_waitcnt lgkmcnt(0)
	v_mfma_f32_16x16x32_bf16 v[128:131], v[132:135], v[200:203], v[128:131]
	v_mfma_f32_16x16x32_bf16 v[124:127], v[154:157], v[200:203], v[124:127]
	v_mfma_f32_16x16x32_bf16 v[112:115], v[132:135], v[208:211], v[112:115]
	v_mfma_f32_16x16x32_bf16 v[108:111], v[154:157], v[208:211], v[108:111]
	v_mfma_f32_16x16x32_bf16 v[96:99], v[132:135], v[232:235], v[96:99]
	v_mfma_f32_16x16x32_bf16 v[92:95], v[154:157], v[232:235], v[92:95]
	v_mfma_f32_16x16x32_bf16 v[80:83], v[132:135], v[240:243], v[80:83]
	v_mfma_f32_16x16x32_bf16 v[76:79], v[154:157], v[240:243], v[76:79]
	v_mfma_f32_16x16x32_bf16 v[128:131], v[136:139], v[204:207], v[128:131]
	v_mfma_f32_16x16x32_bf16 v[124:127], v[158:161], v[204:207], v[124:127]
	v_mfma_f32_16x16x32_bf16 v[112:115], v[136:139], v[212:215], v[112:115]
	v_mfma_f32_16x16x32_bf16 v[108:111], v[158:161], v[212:215], v[108:111]
	v_mfma_f32_16x16x32_bf16 v[96:99], v[136:139], v[236:239], v[96:99]
	v_mfma_f32_16x16x32_bf16 v[92:95], v[158:161], v[236:239], v[92:95]
	v_mfma_f32_16x16x32_bf16 v[80:83], v[136:139], v[244:247], v[80:83]
	v_mfma_f32_16x16x32_bf16 v[76:79], v[158:161], v[244:247], v[76:79]
	v_mfma_f32_16x16x32_bf16 v[120:123], v[184:187], v[200:203], v[120:123]
	v_mfma_f32_16x16x32_bf16 v[116:119], v[192:195], v[200:203], v[116:119]
	v_mfma_f32_16x16x32_bf16 v[104:107], v[184:187], v[208:211], v[104:107]
	v_mfma_f32_16x16x32_bf16 v[100:103], v[192:195], v[208:211], v[100:103]
	v_mfma_f32_16x16x32_bf16 v[88:91], v[184:187], v[232:235], v[88:91]
	v_mfma_f32_16x16x32_bf16 v[84:87], v[192:195], v[232:235], v[84:87]
	v_mfma_f32_16x16x32_bf16 v[72:75], v[184:187], v[240:243], v[72:75]
	v_mfma_f32_16x16x32_bf16 v[68:71], v[192:195], v[240:243], v[68:71]
	v_mfma_f32_16x16x32_bf16 v[120:123], v[188:191], v[204:207], v[120:123]
	v_mfma_f32_16x16x32_bf16 v[116:119], v[196:199], v[204:207], v[116:119]
	v_mfma_f32_16x16x32_bf16 v[104:107], v[188:191], v[212:215], v[104:107]
	v_mfma_f32_16x16x32_bf16 v[100:103], v[196:199], v[212:215], v[100:103]
	v_mfma_f32_16x16x32_bf16 v[88:91], v[188:191], v[236:239], v[88:91]
	v_mfma_f32_16x16x32_bf16 v[84:87], v[196:199], v[236:239], v[84:87]
	v_mfma_f32_16x16x32_bf16 v[72:75], v[188:191], v[244:247], v[72:75]
	v_mfma_f32_16x16x32_bf16 v[68:71], v[196:199], v[244:247], v[68:71]
	s_barrier
	s_add_i32 s34, s34, s15
	v_lshl_add_u64 v[216:217], s[10:11], 0, v[142:143]
	s_mov_b32 m0, s34
	ds_read_b128 v[200:203], v182 offset:16384
	ds_read_b128 v[204:207], v182 offset:17408
	ds_read_b128 v[208:211], v182 offset:18432
	ds_read_b128 v[212:215], v182 offset:19456
	ds_read_b128 v[232:235], v182 offset:20480
	ds_read_b128 v[236:239], v182 offset:21504
	ds_read_b128 v[240:243], v182 offset:22528
	ds_read_b128 v[244:247], v182 offset:23552
	global_load_lds_dwordx4 v[216:217], off
	s_add_i32 m0, s34, 0x2000
	s_add_u32 s34, s10, 0x100000
	v_lshl_add_u64 v[220:221], s[10:11], 0, v[146:147]
	s_addc_u32 s35, s11, 0
	s_add_i32 s40, s40, s15
	global_load_lds_dwordx4 v[220:221], off
	v_lshl_add_u64 v[172:173], s[34:35], 0, v[142:143]
	s_mov_b32 m0, s40
	v_lshl_add_u64 v[174:175], s[12:13], 0, v[144:145]
	global_load_lds_dwordx4 v[172:173], off
	v_lshl_add_u64 v[172:173], s[34:35], 0, v[146:147]
	s_add_i32 m0, s40, 0x2000
	s_nop 0
	global_load_lds_dwordx4 v[172:173], off
	v_lshl_add_u64 v[172:173], s[12:13], 0, v[140:141]
	s_mov_b32 m0, s16
	s_nop 0
	global_load_lds_dwordx4 v[172:173], off
	s_mov_b32 m0, s17
	s_nop 0
	global_load_lds_dwordx4 v[174:175], off
	s_waitcnt vmcnt(8)
	s_waitcnt lgkmcnt(0)
	s_barrier
	s_waitcnt lgkmcnt(0)
	v_mfma_f32_16x16x32_bf16 v[64:67], v[132:135], v[200:203], v[64:67]
	v_mfma_f32_16x16x32_bf16 v[60:63], v[154:157], v[200:203], v[60:63]
	v_mfma_f32_16x16x32_bf16 v[48:51], v[132:135], v[208:211], v[48:51]
	v_mfma_f32_16x16x32_bf16 v[44:47], v[154:157], v[208:211], v[44:47]
	v_mfma_f32_16x16x32_bf16 v[30:33], v[132:135], v[232:235], v[30:33]
	v_mfma_f32_16x16x32_bf16 v[26:29], v[154:157], v[232:235], v[26:29]
	v_mfma_f32_16x16x32_bf16 v[14:17], v[132:135], v[240:243], v[14:17]
	v_mfma_f32_16x16x32_bf16 v[10:13], v[154:157], v[240:243], v[10:13]
	v_mfma_f32_16x16x32_bf16 v[64:67], v[136:139], v[204:207], v[64:67]
	v_mfma_f32_16x16x32_bf16 v[60:63], v[158:161], v[204:207], v[60:63]
	v_mfma_f32_16x16x32_bf16 v[48:51], v[136:139], v[212:215], v[48:51]
	v_mfma_f32_16x16x32_bf16 v[44:47], v[158:161], v[212:215], v[44:47]
	v_mfma_f32_16x16x32_bf16 v[30:33], v[136:139], v[236:239], v[30:33]
	v_mfma_f32_16x16x32_bf16 v[26:29], v[158:161], v[236:239], v[26:29]
	v_mfma_f32_16x16x32_bf16 v[14:17], v[136:139], v[244:247], v[14:17]
	v_mfma_f32_16x16x32_bf16 v[10:13], v[158:161], v[244:247], v[10:13]
	v_mfma_f32_16x16x32_bf16 v[56:59], v[184:187], v[200:203], v[56:59]
	v_mfma_f32_16x16x32_bf16 v[52:55], v[192:195], v[200:203], v[52:55]
	v_mfma_f32_16x16x32_bf16 v[40:43], v[184:187], v[208:211], v[40:43]
	v_mfma_f32_16x16x32_bf16 v[36:39], v[192:195], v[208:211], v[36:39]
	v_mfma_f32_16x16x32_bf16 v[22:25], v[184:187], v[232:235], v[22:25]
	v_mfma_f32_16x16x32_bf16 v[18:21], v[192:195], v[232:235], v[18:21]
	v_mfma_f32_16x16x32_bf16 v[6:9], v[184:187], v[240:243], v[6:9]
	v_mfma_f32_16x16x32_bf16 v[2:5], v[192:195], v[240:243], v[2:5]
	v_mfma_f32_16x16x32_bf16 v[56:59], v[188:191], v[204:207], v[56:59]
	v_mfma_f32_16x16x32_bf16 v[52:55], v[196:199], v[204:207], v[52:55]
	v_mfma_f32_16x16x32_bf16 v[40:43], v[188:191], v[212:215], v[40:43]
	v_mfma_f32_16x16x32_bf16 v[36:39], v[196:199], v[212:215], v[36:39]
	v_mfma_f32_16x16x32_bf16 v[22:25], v[188:191], v[236:239], v[22:25]
	v_mfma_f32_16x16x32_bf16 v[18:21], v[196:199], v[236:239], v[18:21]
	v_mfma_f32_16x16x32_bf16 v[6:9], v[188:191], v[244:247], v[6:9]
	v_mfma_f32_16x16x32_bf16 v[2:5], v[196:199], v[244:247], v[2:5]
	s_barrier
	s_add_i32 s34, 0, 0x18000
	s_add_i32 s35, 0, 0x1c000
	v_add_u32_e32 v158, s34, v162
	v_add_u32_e32 v176, s35, v162
	ds_read_b128 v[132:135], v158
	ds_read_b128 v[136:139], v158 offset:1024
	ds_read_b128 v[154:157], v158 offset:2048
	ds_read_b128 v[158:161], v158 offset:3072
	ds_read_b128 v[184:187], v176
	ds_read_b128 v[188:191], v176 offset:1024
	ds_read_b128 v[192:195], v176 offset:2048
	ds_read_b128 v[196:199], v176 offset:3072
	s_add_u32 s12, s12, 0x100000
	s_addc_u32 s13, s13, 0
	s_mov_b32 m0, s18
	v_lshl_add_u64 v[176:177], s[12:13], 0, v[140:141]
	ds_read_b128 v[200:203], v182 offset:32768
	ds_read_b128 v[204:207], v182 offset:33792
	ds_read_b128 v[208:211], v182 offset:34816
	ds_read_b128 v[212:215], v182 offset:35840
	ds_read_b128 v[232:235], v182 offset:36864
	ds_read_b128 v[236:239], v182 offset:37888
	ds_read_b128 v[240:243], v182 offset:38912
	ds_read_b128 v[244:247], v182 offset:39936
	global_load_lds_dwordx4 v[176:177], off
	v_lshl_add_u64 v[176:177], s[12:13], 0, v[144:145]
	s_mov_b32 m0, s19
	s_nop 0
	global_load_lds_dwordx4 v[176:177], off
	s_waitcnt vmcnt(8)
	s_waitcnt lgkmcnt(0)
	s_barrier
	s_waitcnt lgkmcnt(0)
	v_mfma_f32_16x16x32_bf16 v[128:131], v[132:135], v[200:203], v[128:131]
	v_mfma_f32_16x16x32_bf16 v[124:127], v[154:157], v[200:203], v[124:127]
	v_mfma_f32_16x16x32_bf16 v[112:115], v[132:135], v[208:211], v[112:115]
	v_mfma_f32_16x16x32_bf16 v[108:111], v[154:157], v[208:211], v[108:111]
	v_mfma_f32_16x16x32_bf16 v[96:99], v[132:135], v[232:235], v[96:99]
	v_mfma_f32_16x16x32_bf16 v[92:95], v[154:157], v[232:235], v[92:95]
	v_mfma_f32_16x16x32_bf16 v[80:83], v[132:135], v[240:243], v[80:83]
	v_mfma_f32_16x16x32_bf16 v[76:79], v[154:157], v[240:243], v[76:79]
	v_mfma_f32_16x16x32_bf16 v[128:131], v[136:139], v[204:207], v[128:131]
	v_mfma_f32_16x16x32_bf16 v[124:127], v[158:161], v[204:207], v[124:127]
	v_mfma_f32_16x16x32_bf16 v[112:115], v[136:139], v[212:215], v[112:115]
	v_mfma_f32_16x16x32_bf16 v[108:111], v[158:161], v[212:215], v[108:111]
	v_mfma_f32_16x16x32_bf16 v[96:99], v[136:139], v[236:239], v[96:99]
	v_mfma_f32_16x16x32_bf16 v[92:95], v[158:161], v[236:239], v[92:95]
	v_mfma_f32_16x16x32_bf16 v[80:83], v[136:139], v[244:247], v[80:83]
	v_mfma_f32_16x16x32_bf16 v[76:79], v[158:161], v[244:247], v[76:79]
	v_mfma_f32_16x16x32_bf16 v[120:123], v[184:187], v[200:203], v[120:123]
	v_mfma_f32_16x16x32_bf16 v[116:119], v[192:195], v[200:203], v[116:119]
	v_mfma_f32_16x16x32_bf16 v[104:107], v[184:187], v[208:211], v[104:107]
	v_mfma_f32_16x16x32_bf16 v[100:103], v[192:195], v[208:211], v[100:103]
	v_mfma_f32_16x16x32_bf16 v[88:91], v[184:187], v[232:235], v[88:91]
	v_mfma_f32_16x16x32_bf16 v[84:87], v[192:195], v[232:235], v[84:87]
	v_mfma_f32_16x16x32_bf16 v[72:75], v[184:187], v[240:243], v[72:75]
	v_mfma_f32_16x16x32_bf16 v[68:71], v[192:195], v[240:243], v[68:71]
	v_mfma_f32_16x16x32_bf16 v[120:123], v[188:191], v[204:207], v[120:123]
	v_mfma_f32_16x16x32_bf16 v[116:119], v[196:199], v[204:207], v[116:119]
	v_mfma_f32_16x16x32_bf16 v[104:107], v[188:191], v[212:215], v[104:107]
	v_mfma_f32_16x16x32_bf16 v[100:103], v[196:199], v[212:215], v[100:103]
	v_mfma_f32_16x16x32_bf16 v[88:91], v[188:191], v[236:239], v[88:91]
	v_mfma_f32_16x16x32_bf16 v[84:87], v[196:199], v[236:239], v[84:87]
	v_mfma_f32_16x16x32_bf16 v[72:75], v[188:191], v[244:247], v[72:75]
	v_mfma_f32_16x16x32_bf16 v[68:71], v[196:199], v[244:247], v[68:71]
	s_barrier
	s_add_i32 s12, s34, s15
	v_lshl_add_u64 v[176:177], v[216:217], 0, s[2:3]
	s_mov_b32 m0, s12
	ds_read_b128 v[200:203], v182 offset:49152
	ds_read_b128 v[204:207], v182 offset:50176
	ds_read_b128 v[208:211], v182 offset:51200
	ds_read_b128 v[212:215], v182 offset:52224
	ds_read_b128 v[232:235], v182 offset:53248
	ds_read_b128 v[236:239], v182 offset:54272
	ds_read_b128 v[240:243], v182 offset:55296
	ds_read_b128 v[244:247], v182 offset:56320
	global_load_lds_dwordx4 v[176:177], off
	s_add_i32 m0, s12, 0x2000
	s_add_u32 s10, s10, 0x100080
	v_lshl_add_u64 v[176:177], v[220:221], 0, s[2:3]
	s_addc_u32 s11, s11, 0
	s_add_i32 s12, s35, s15
	global_load_lds_dwordx4 v[176:177], off
	v_lshl_add_u64 v[176:177], s[10:11], 0, v[142:143]
	s_mov_b32 m0, s12
	v_lshl_add_u64 v[172:173], v[172:173], 0, s[2:3]
	global_load_lds_dwordx4 v[176:177], off
	v_lshl_add_u64 v[176:177], s[10:11], 0, v[146:147]
	s_add_i32 m0, s12, 0x2000
	s_nop 0
	global_load_lds_dwordx4 v[176:177], off
	s_mov_b32 m0, s20
	s_nop 0
	global_load_lds_dwordx4 v[172:173], off
	v_lshl_add_u64 v[172:173], v[174:175], 0, s[2:3]
	s_mov_b32 m0, s21
	s_nop 0
	global_load_lds_dwordx4 v[172:173], off
	s_waitcnt vmcnt(8)
	s_waitcnt lgkmcnt(0)
	s_barrier
	s_waitcnt lgkmcnt(0)
	v_mfma_f32_16x16x32_bf16 v[64:67], v[132:135], v[200:203], v[64:67]
	v_mfma_f32_16x16x32_bf16 v[60:63], v[154:157], v[200:203], v[60:63]
	v_mfma_f32_16x16x32_bf16 v[48:51], v[132:135], v[208:211], v[48:51]
	v_mfma_f32_16x16x32_bf16 v[44:47], v[154:157], v[208:211], v[44:47]
	v_mfma_f32_16x16x32_bf16 v[30:33], v[132:135], v[232:235], v[30:33]
	v_mfma_f32_16x16x32_bf16 v[26:29], v[154:157], v[232:235], v[26:29]
	v_mfma_f32_16x16x32_bf16 v[14:17], v[132:135], v[240:243], v[14:17]
	v_mfma_f32_16x16x32_bf16 v[10:13], v[154:157], v[240:243], v[10:13]
	v_mfma_f32_16x16x32_bf16 v[64:67], v[136:139], v[204:207], v[64:67]
	v_mfma_f32_16x16x32_bf16 v[60:63], v[158:161], v[204:207], v[60:63]
	v_mfma_f32_16x16x32_bf16 v[48:51], v[136:139], v[212:215], v[48:51]
	v_mfma_f32_16x16x32_bf16 v[44:47], v[158:161], v[212:215], v[44:47]
	v_mfma_f32_16x16x32_bf16 v[30:33], v[136:139], v[236:239], v[30:33]
	v_mfma_f32_16x16x32_bf16 v[26:29], v[158:161], v[236:239], v[26:29]
	v_mfma_f32_16x16x32_bf16 v[14:17], v[136:139], v[244:247], v[14:17]
	v_mfma_f32_16x16x32_bf16 v[10:13], v[158:161], v[244:247], v[10:13]
	v_mfma_f32_16x16x32_bf16 v[56:59], v[184:187], v[200:203], v[56:59]
	v_mfma_f32_16x16x32_bf16 v[52:55], v[192:195], v[200:203], v[52:55]
	v_mfma_f32_16x16x32_bf16 v[40:43], v[184:187], v[208:211], v[40:43]
	v_mfma_f32_16x16x32_bf16 v[36:39], v[192:195], v[208:211], v[36:39]
	v_mfma_f32_16x16x32_bf16 v[22:25], v[184:187], v[232:235], v[22:25]
	v_mfma_f32_16x16x32_bf16 v[18:21], v[192:195], v[232:235], v[18:21]
	v_mfma_f32_16x16x32_bf16 v[6:9], v[184:187], v[240:243], v[6:9]
	v_mfma_f32_16x16x32_bf16 v[2:5], v[192:195], v[240:243], v[2:5]
	v_mfma_f32_16x16x32_bf16 v[56:59], v[188:191], v[204:207], v[56:59]
	v_mfma_f32_16x16x32_bf16 v[52:55], v[196:199], v[204:207], v[52:55]
	v_mfma_f32_16x16x32_bf16 v[40:43], v[188:191], v[212:215], v[40:43]
	v_mfma_f32_16x16x32_bf16 v[36:39], v[196:199], v[212:215], v[36:39]
	v_mfma_f32_16x16x32_bf16 v[22:25], v[188:191], v[236:239], v[22:25]
	v_mfma_f32_16x16x32_bf16 v[18:21], v[196:199], v[236:239], v[18:21]
	v_mfma_f32_16x16x32_bf16 v[6:9], v[188:191], v[244:247], v[6:9]
	v_mfma_f32_16x16x32_bf16 v[2:5], v[196:199], v[244:247], v[2:5]
	s_barrier
	s_add_i32 s29, s29, 2
	s_add_u32 s8, s8, 0x100
	s_addc_u32 s9, s9, 0
	s_add_u32 s27, s27, 0x100
	s_addc_u32 s28, s28, 0
	s_cmp_gt_u32 s29, 61
	s_cbranch_scc0 .LBB0_104
	s_and_b64 vcc, exec, s[66:67]
	s_cbranch_vccnz .LBB0_109
	v_lshl_add_u32 v154, s6, 8, v35
	s_cmp_gt_i32 s76, 7
	s_mov_b64 s[6:7], -1
	s_cbranch_scc1 .LBB0_110

.LBB0_200:
	s_add_u32 s10, s8, 0xfff80080
	s_addc_u32 s11, s9, -1
	s_add_i32 s35, 0, 0x10000
	s_cmp_eq_u32 s34, 28
	s_cselect_b32 s13, s7, s11
	s_cselect_b32 s12, s26, s10
	s_cselect_b32 s11, s27, s31
	s_cselect_b32 s10, s28, s29
	s_add_i32 s40, 0, 0x14000
	v_add_u32_e32 v2, s35, v194
	v_add_u32_e32 v14, s40, v194
	ds_read_b128 v[18:21], v2
	ds_read_b128 v[22:25], v2 offset:1024
	ds_read_b128 v[26:29], v2 offset:2048
	ds_read_b128 v[30:33], v2 offset:3072
	ds_read_b128 v[2:5], v14
	ds_read_b128 v[6:9], v14 offset:1024
	ds_read_b128 v[10:13], v14 offset:2048
	ds_read_b128 v[14:17], v14 offset:3072
	v_lshl_add_u64 v[196:197], s[8:9], 0, v[182:183]
	s_add_i32 m0, s18, 0xc000
	ds_read_b128 v[186:189], v206
	ds_read_b128 v[190:193], v206 offset:1024
	ds_read_b128 v[208:211], v206 offset:2048
	ds_read_b128 v[212:215], v206 offset:3072
	ds_read_b128 v[232:235], v206 offset:4096
	ds_read_b128 v[236:239], v206 offset:5120
	ds_read_b128 v[240:243], v206 offset:6144
	ds_read_b128 v[244:247], v206 offset:7168
	global_load_lds_dwordx4 v[196:197], off
	v_lshl_add_u64 v[196:197], s[8:9], 0, v[184:185]
	s_add_i32 m0, s18, 0xe000
	s_nop 0
	global_load_lds_dwordx4 v[196:197], off
	s_waitcnt vmcnt(8)
	s_waitcnt lgkmcnt(0)
	s_barrier
	s_waitcnt lgkmcnt(0)
	v_mfma_f32_16x16x128_f8f6f4 v[160:163], v[18:25], v[186:193], v[160:163]
	v_mfma_f32_16x16x128_f8f6f4 v[156:159], v[26:33], v[186:193], v[156:159]
	v_mfma_f32_16x16x128_f8f6f4 v[144:147], v[18:25], v[208:215], v[144:147]
	v_mfma_f32_16x16x128_f8f6f4 v[140:143], v[26:33], v[208:215], v[140:143]
	v_mfma_f32_16x16x128_f8f6f4 v[128:131], v[18:25], v[232:239], v[128:131]
	v_mfma_f32_16x16x128_f8f6f4 v[124:127], v[26:33], v[232:239], v[124:127]
	v_mfma_f32_16x16x128_f8f6f4 v[112:115], v[18:25], v[240:247], v[112:115]
	v_mfma_f32_16x16x128_f8f6f4 v[108:111], v[26:33], v[240:247], v[108:111]
	v_mfma_f32_16x16x128_f8f6f4 v[152:155], v[2:9], v[186:193], v[152:155]
	v_mfma_f32_16x16x128_f8f6f4 v[148:151], v[10:17], v[186:193], v[148:151]
	v_mfma_f32_16x16x128_f8f6f4 v[136:139], v[2:9], v[208:215], v[136:139]
	v_mfma_f32_16x16x128_f8f6f4 v[132:135], v[10:17], v[208:215], v[132:135]
	v_mfma_f32_16x16x128_f8f6f4 v[120:123], v[2:9], v[232:239], v[120:123]
	v_mfma_f32_16x16x128_f8f6f4 v[116:119], v[10:17], v[232:239], v[116:119]
	v_mfma_f32_16x16x128_f8f6f4 v[104:107], v[2:9], v[240:247], v[104:107]
	v_mfma_f32_16x16x128_f8f6f4 v[100:103], v[10:17], v[240:247], v[100:103]
	s_barrier
	s_add_i32 s35, s35, s15
	v_lshl_add_u64 v[186:187], s[10:11], 0, v[174:175]
	s_mov_b32 m0, s35
	ds_read_b128 v[208:211], v206 offset:16384
	ds_read_b128 v[212:215], v206 offset:17408
	ds_read_b128 v[232:235], v206 offset:18432
	ds_read_b128 v[236:239], v206 offset:19456
	ds_read_b128 v[240:243], v206 offset:20480
	ds_read_b128 v[244:247], v206 offset:21504
	ds_read_b128 v[196:199], v206 offset:22528
	ds_read_b128 v[200:203], v206 offset:23552
	global_load_lds_dwordx4 v[186:187], off
	s_add_i32 m0, s35, 0x2000
	s_add_u32 s76, s10, 0x80000
	v_lshl_add_u64 v[188:189], s[10:11], 0, v[178:179]
	s_addc_u32 s77, s11, 0
	s_add_i32 s35, s40, s15
	global_load_lds_dwordx4 v[188:189], off
	v_lshl_add_u64 v[190:191], s[76:77], 0, v[174:175]
	s_mov_b32 m0, s35
	v_lshl_add_u64 v[192:193], s[12:13], 0, v[176:177]
	global_load_lds_dwordx4 v[190:191], off
	v_lshl_add_u64 v[190:191], s[76:77], 0, v[178:179]
	s_add_i32 m0, s35, 0x2000
	s_nop 0
	global_load_lds_dwordx4 v[190:191], off
	v_lshl_add_u64 v[190:191], s[12:13], 0, v[172:173]
	s_mov_b32 m0, s18
	s_nop 0
	global_load_lds_dwordx4 v[190:191], off
	s_mov_b32 m0, s19
	s_nop 0
	global_load_lds_dwordx4 v[192:193], off
	s_waitcnt vmcnt(8)
	s_waitcnt lgkmcnt(0)
	s_barrier
	s_waitcnt lgkmcnt(0)
	v_mfma_f32_16x16x128_f8f6f4 v[96:99], v[18:25], v[208:215], v[96:99]
	v_mfma_f32_16x16x128_f8f6f4 v[92:95], v[26:33], v[208:215], v[92:95]
	v_mfma_f32_16x16x128_f8f6f4 v[80:83], v[18:25], v[232:239], v[80:83]
	v_mfma_f32_16x16x128_f8f6f4 v[76:79], v[26:33], v[232:239], v[76:79]
	v_mfma_f32_16x16x128_f8f6f4 v[64:67], v[18:25], v[240:247], v[64:67]
	v_mfma_f32_16x16x128_f8f6f4 v[60:63], v[26:33], v[240:247], v[60:63]
	v_mfma_f32_16x16x128_f8f6f4 v[48:51], v[18:25], v[196:203], v[48:51]
	v_mfma_f32_16x16x128_f8f6f4 v[44:47], v[26:33], v[196:203], v[44:47]
	v_mfma_f32_16x16x128_f8f6f4 v[88:91], v[2:9], v[208:215], v[88:91]
	v_mfma_f32_16x16x128_f8f6f4 v[84:87], v[10:17], v[208:215], v[84:87]
	v_mfma_f32_16x16x128_f8f6f4 v[72:75], v[2:9], v[232:239], v[72:75]
	v_mfma_f32_16x16x128_f8f6f4 v[68:71], v[10:17], v[232:239], v[68:71]
	v_mfma_f32_16x16x128_f8f6f4 v[56:59], v[2:9], v[240:247], v[56:59]
	v_mfma_f32_16x16x128_f8f6f4 v[52:55], v[10:17], v[240:247], v[52:55]
	v_mfma_f32_16x16x128_f8f6f4 v[40:43], v[2:9], v[196:203], v[40:43]
	v_mfma_f32_16x16x128_f8f6f4 v[36:39], v[10:17], v[196:203], v[36:39]
	s_barrier
	s_add_i32 s35, 0, 0x18000
	s_add_i32 s40, 0, 0x1c000
	v_add_u32_e32 v14, s35, v194
	v_add_u32_e32 v30, s40, v194
	ds_read_b128 v[2:5], v14
	ds_read_b128 v[6:9], v14 offset:1024
	ds_read_b128 v[10:13], v14 offset:2048
	ds_read_b128 v[14:17], v14 offset:3072
	ds_read_b128 v[18:21], v30
	ds_read_b128 v[22:25], v30 offset:1024
	ds_read_b128 v[26:29], v30 offset:2048
	ds_read_b128 v[30:33], v30 offset:3072
	s_add_u32 s12, s12, 0x80000
	s_addc_u32 s13, s13, 0
	s_mov_b32 m0, s20
	v_lshl_add_u64 v[216:217], s[12:13], 0, v[172:173]
	ds_read_b128 v[196:199], v206 offset:32768
	ds_read_b128 v[200:203], v206 offset:33792
	ds_read_b128 v[208:211], v206 offset:34816
	ds_read_b128 v[212:215], v206 offset:35840
	ds_read_b128 v[232:235], v206 offset:36864
	ds_read_b128 v[236:239], v206 offset:37888
	ds_read_b128 v[240:243], v206 offset:38912
	ds_read_b128 v[244:247], v206 offset:39936
	global_load_lds_dwordx4 v[216:217], off
	v_lshl_add_u64 v[216:217], s[12:13], 0, v[176:177]
	s_mov_b32 m0, s21
	s_nop 0
	global_load_lds_dwordx4 v[216:217], off
	s_waitcnt vmcnt(8)
	s_waitcnt lgkmcnt(0)
	s_barrier
	s_waitcnt lgkmcnt(0)
	v_mfma_f32_16x16x128_f8f6f4 v[160:163], v[2:9], v[196:203], v[160:163]
	v_mfma_f32_16x16x128_f8f6f4 v[156:159], v[10:17], v[196:203], v[156:159]
	v_mfma_f32_16x16x128_f8f6f4 v[144:147], v[2:9], v[208:215], v[144:147]
	v_mfma_f32_16x16x128_f8f6f4 v[140:143], v[10:17], v[208:215], v[140:143]
	v_mfma_f32_16x16x128_f8f6f4 v[128:131], v[2:9], v[232:239], v[128:131]
	v_mfma_f32_16x16x128_f8f6f4 v[124:127], v[10:17], v[232:239], v[124:127]
	v_mfma_f32_16x16x128_f8f6f4 v[112:115], v[2:9], v[240:247], v[112:115]
	v_mfma_f32_16x16x128_f8f6f4 v[108:111], v[10:17], v[240:247], v[108:111]
	v_mfma_f32_16x16x128_f8f6f4 v[152:155], v[18:25], v[196:203], v[152:155]
	v_mfma_f32_16x16x128_f8f6f4 v[148:151], v[26:33], v[196:203], v[148:151]
	v_mfma_f32_16x16x128_f8f6f4 v[136:139], v[18:25], v[208:215], v[136:139]
	v_mfma_f32_16x16x128_f8f6f4 v[132:135], v[26:33], v[208:215], v[132:135]
	v_mfma_f32_16x16x128_f8f6f4 v[120:123], v[18:25], v[232:239], v[120:123]
	v_mfma_f32_16x16x128_f8f6f4 v[116:119], v[26:33], v[232:239], v[116:119]
	v_mfma_f32_16x16x128_f8f6f4 v[104:107], v[18:25], v[240:247], v[104:107]
	v_mfma_f32_16x16x128_f8f6f4 v[100:103], v[26:33], v[240:247], v[100:103]
	s_barrier
	s_add_i32 s12, s35, s15
	v_lshl_add_u64 v[186:187], v[186:187], 0, s[2:3]
	s_mov_b32 m0, s12
	ds_read_b128 v[196:199], v206 offset:49152
	ds_read_b128 v[200:203], v206 offset:50176
	ds_read_b128 v[208:211], v206 offset:51200
	ds_read_b128 v[212:215], v206 offset:52224
	ds_read_b128 v[232:235], v206 offset:53248
	ds_read_b128 v[236:239], v206 offset:54272
	ds_read_b128 v[240:243], v206 offset:55296
	ds_read_b128 v[244:247], v206 offset:56320
	global_load_lds_dwordx4 v[186:187], off
	s_add_i32 m0, s12, 0x2000
	s_add_u32 s10, s10, 0x80080
	v_lshl_add_u64 v[186:187], v[188:189], 0, s[2:3]
	s_addc_u32 s11, s11, 0
	s_add_i32 s12, s40, s15
	global_load_lds_dwordx4 v[186:187], off
	v_lshl_add_u64 v[186:187], s[10:11], 0, v[174:175]
	s_mov_b32 m0, s12
	s_nop 0
	global_load_lds_dwordx4 v[186:187], off
	v_lshl_add_u64 v[186:187], s[10:11], 0, v[178:179]
	s_add_i32 m0, s12, 0x2000
	s_nop 0
	global_load_lds_dwordx4 v[186:187], off
	v_lshl_add_u64 v[186:187], v[190:191], 0, s[2:3]
	s_mov_b32 m0, s22
	s_nop 0
	global_load_lds_dwordx4 v[186:187], off
	v_lshl_add_u64 v[186:187], v[192:193], 0, s[2:3]
	s_mov_b32 m0, s23
	s_nop 0
	global_load_lds_dwordx4 v[186:187], off
	s_waitcnt vmcnt(8)
	s_waitcnt lgkmcnt(0)
	s_barrier
	s_waitcnt lgkmcnt(0)
	v_mfma_f32_16x16x128_f8f6f4 v[96:99], v[2:9], v[196:203], v[96:99]
	v_mfma_f32_16x16x128_f8f6f4 v[92:95], v[10:17], v[196:203], v[92:95]
	v_mfma_f32_16x16x128_f8f6f4 v[80:83], v[2:9], v[208:215], v[80:83]
	v_mfma_f32_16x16x128_f8f6f4 v[76:79], v[10:17], v[208:215], v[76:79]
	v_mfma_f32_16x16x128_f8f6f4 v[64:67], v[2:9], v[232:239], v[64:67]
	v_mfma_f32_16x16x128_f8f6f4 v[60:63], v[10:17], v[232:239], v[60:63]
	v_mfma_f32_16x16x128_f8f6f4 v[48:51], v[2:9], v[240:247], v[48:51]
	v_mfma_f32_16x16x128_f8f6f4 v[44:47], v[10:17], v[240:247], v[44:47]
	v_mfma_f32_16x16x128_f8f6f4 v[88:91], v[18:25], v[196:203], v[88:91]
	v_mfma_f32_16x16x128_f8f6f4 v[84:87], v[26:33], v[196:203], v[84:87]
	v_mfma_f32_16x16x128_f8f6f4 v[72:75], v[18:25], v[208:215], v[72:75]
	v_mfma_f32_16x16x128_f8f6f4 v[68:71], v[26:33], v[208:215], v[68:71]
	v_mfma_f32_16x16x128_f8f6f4 v[56:59], v[18:25], v[232:239], v[56:59]
	v_mfma_f32_16x16x128_f8f6f4 v[52:55], v[26:33], v[232:239], v[52:55]
	v_mfma_f32_16x16x128_f8f6f4 v[40:43], v[18:25], v[240:247], v[40:43]
	v_mfma_f32_16x16x128_f8f6f4 v[36:39], v[26:33], v[240:247], v[36:39]
	s_barrier
	s_add_i32 s34, s34, 2
	s_add_u32 s8, s8, 0x100
	s_addc_u32 s9, s9, 0
	s_add_u32 s29, s29, 0x100
	s_addc_u32 s31, s31, 0
	s_cmp_gt_u32 s34, 29
	s_cbranch_scc0 .LBB0_200
	s_and_b64 vcc, exec, s[66:67]
	s_cbranch_vccz .LBB0_203
	s_barrier

.LBB0_1446:
	s_add_u32 s10, s26, s8
	s_addc_u32 s11, s27, s9
	s_add_u32 s10, s10, 0x55a00100
	s_addc_u32 s11, s11, 0
	s_add_u32 s29, s24, s8
	s_addc_u32 s30, s25, s9
	s_add_i32 s31, 0, 0x10000
	s_cmpk_eq_i32 s8, 0xf00
	s_cselect_b32 s13, s7, s11
	s_cselect_b32 s12, s6, s10
	v_add_u32_e32 v1, s31, v146
	s_cselect_b32 s11, s1, s30
	s_cselect_b32 s10, s0, s29
	s_add_i32 s29, 0, 0x14000
	ds_read_b128 v[148:151], v1
	ds_read_b128 v[152:155], v1 offset:1024
	ds_read_b128 v[156:159], v1 offset:2048
	ds_read_b128 v[160:163], v1 offset:3072
	v_add_u32_e32 v1, s29, v146
	ds_read_b128 v[172:175], v1
	ds_read_b128 v[176:179], v1 offset:1024
	ds_read_b128 v[180:183], v1 offset:2048
	ds_read_b128 v[184:187], v1 offset:3072
	v_lshl_add_u64 v[216:217], v[144:145], 0, s[8:9]
	s_add_i32 m0, s16, 0xc000
	ds_read_b128 v[188:191], v147
	ds_read_b128 v[192:195], v147 offset:1024
	ds_read_b128 v[196:199], v147 offset:2048
	ds_read_b128 v[200:203], v147 offset:3072
	ds_read_b128 v[204:207], v147 offset:4096
	ds_read_b128 v[208:211], v147 offset:5120
	ds_read_b128 v[212:215], v147 offset:6144
	ds_read_b128 v[232:235], v147 offset:7168
	global_load_lds_dwordx4 v[216:217], off
	v_lshl_add_u64 v[216:217], v[142:143], 0, s[8:9]
	s_add_i32 m0, s16, 0xe000
	s_nop 0
	global_load_lds_dwordx4 v[216:217], off
	s_waitcnt vmcnt(8)
	s_waitcnt lgkmcnt(0)
	s_barrier
	s_waitcnt lgkmcnt(0)
	v_mfma_f32_16x16x32_bf16 v[128:131], v[148:151], v[188:191], v[128:131]
	v_mfma_f32_16x16x32_bf16 v[124:127], v[156:159], v[188:191], v[124:127]
	v_mfma_f32_16x16x32_bf16 v[116:119], v[148:151], v[196:199], v[116:119]
	v_mfma_f32_16x16x32_bf16 v[108:111], v[156:159], v[196:199], v[108:111]
	v_mfma_f32_16x16x32_bf16 v[100:103], v[148:151], v[204:207], v[100:103]
	v_mfma_f32_16x16x32_bf16 v[92:95], v[156:159], v[204:207], v[92:95]
	v_mfma_f32_16x16x32_bf16 v[84:87], v[148:151], v[212:215], v[84:87]
	v_mfma_f32_16x16x32_bf16 v[76:79], v[156:159], v[212:215], v[76:79]
	v_mfma_f32_16x16x32_bf16 v[128:131], v[152:155], v[192:195], v[128:131]
	v_mfma_f32_16x16x32_bf16 v[124:127], v[160:163], v[192:195], v[124:127]
	v_mfma_f32_16x16x32_bf16 v[116:119], v[152:155], v[200:203], v[116:119]
	v_mfma_f32_16x16x32_bf16 v[108:111], v[160:163], v[200:203], v[108:111]
	v_mfma_f32_16x16x32_bf16 v[100:103], v[152:155], v[208:211], v[100:103]
	v_mfma_f32_16x16x32_bf16 v[92:95], v[160:163], v[208:211], v[92:95]
	v_mfma_f32_16x16x32_bf16 v[84:87], v[152:155], v[232:235], v[84:87]
	v_mfma_f32_16x16x32_bf16 v[76:79], v[160:163], v[232:235], v[76:79]
	v_mfma_f32_16x16x32_bf16 v[120:123], v[172:175], v[188:191], v[120:123]
	v_mfma_f32_16x16x32_bf16 v[112:115], v[180:183], v[188:191], v[112:115]
	v_mfma_f32_16x16x32_bf16 v[104:107], v[172:175], v[196:199], v[104:107]
	v_mfma_f32_16x16x32_bf16 v[96:99], v[180:183], v[196:199], v[96:99]
	v_mfma_f32_16x16x32_bf16 v[88:91], v[172:175], v[204:207], v[88:91]
	v_mfma_f32_16x16x32_bf16 v[80:83], v[180:183], v[204:207], v[80:83]
	v_mfma_f32_16x16x32_bf16 v[72:75], v[172:175], v[212:215], v[72:75]
	v_mfma_f32_16x16x32_bf16 v[68:71], v[180:183], v[212:215], v[68:71]
	v_mfma_f32_16x16x32_bf16 v[120:123], v[176:179], v[192:195], v[120:123]
	v_mfma_f32_16x16x32_bf16 v[112:115], v[184:187], v[192:195], v[112:115]
	v_mfma_f32_16x16x32_bf16 v[104:107], v[176:179], v[200:203], v[104:107]
	v_mfma_f32_16x16x32_bf16 v[96:99], v[184:187], v[200:203], v[96:99]
	v_mfma_f32_16x16x32_bf16 v[88:91], v[176:179], v[208:211], v[88:91]
	v_mfma_f32_16x16x32_bf16 v[80:83], v[184:187], v[208:211], v[80:83]
	v_mfma_f32_16x16x32_bf16 v[72:75], v[176:179], v[232:235], v[72:75]
	v_mfma_f32_16x16x32_bf16 v[68:71], v[184:187], v[232:235], v[68:71]
	s_barrier
	s_add_i32 s30, s31, s15
	v_lshl_add_u64 v[216:217], s[10:11], 0, v[134:135]
	s_mov_b32 m0, s30
	ds_read_b128 v[188:191], v147 offset:16384
	ds_read_b128 v[192:195], v147 offset:17408
	ds_read_b128 v[196:199], v147 offset:18432
	ds_read_b128 v[200:203], v147 offset:19456
	ds_read_b128 v[204:207], v147 offset:20480
	ds_read_b128 v[208:211], v147 offset:21504
	ds_read_b128 v[212:215], v147 offset:22528
	ds_read_b128 v[232:235], v147 offset:23552
	global_load_lds_dwordx4 v[216:217], off
	s_add_i32 m0, s30, 0x2000
	s_add_u32 s30, s10, 0x180000
	v_lshl_add_u64 v[220:221], s[10:11], 0, v[138:139]
	s_addc_u32 s31, s11, 0
	s_add_i32 s29, s29, s15
	global_load_lds_dwordx4 v[220:221], off
	v_lshl_add_u64 v[236:237], s[30:31], 0, v[134:135]
	s_mov_b32 m0, s29
	v_lshl_add_u64 v[238:239], s[12:13], 0, v[136:137]
	global_load_lds_dwordx4 v[236:237], off
	v_lshl_add_u64 v[236:237], s[30:31], 0, v[138:139]
	s_add_i32 m0, s29, 0x2000
	s_nop 0
	global_load_lds_dwordx4 v[236:237], off
	v_lshl_add_u64 v[236:237], s[12:13], 0, v[132:133]
	s_mov_b32 m0, s16
	s_nop 0
	global_load_lds_dwordx4 v[236:237], off
	s_mov_b32 m0, s17
	s_nop 0
	global_load_lds_dwordx4 v[238:239], off
	s_waitcnt vmcnt(8)
	s_waitcnt lgkmcnt(0)
	s_barrier
	s_waitcnt lgkmcnt(0)
	v_mfma_f32_16x16x32_bf16 v[64:67], v[148:151], v[188:191], v[64:67]
	v_mfma_f32_16x16x32_bf16 v[60:63], v[156:159], v[188:191], v[60:63]
	v_mfma_f32_16x16x32_bf16 v[52:55], v[148:151], v[196:199], v[52:55]
	v_mfma_f32_16x16x32_bf16 v[44:47], v[156:159], v[196:199], v[44:47]
	v_mfma_f32_16x16x32_bf16 v[36:39], v[148:151], v[204:207], v[36:39]
	v_mfma_f32_16x16x32_bf16 v[26:29], v[156:159], v[204:207], v[26:29]
	v_mfma_f32_16x16x32_bf16 v[18:21], v[148:151], v[212:215], v[18:21]
	v_mfma_f32_16x16x32_bf16 v[10:13], v[156:159], v[212:215], v[10:13]
	v_mfma_f32_16x16x32_bf16 v[64:67], v[152:155], v[192:195], v[64:67]
	v_mfma_f32_16x16x32_bf16 v[60:63], v[160:163], v[192:195], v[60:63]
	v_mfma_f32_16x16x32_bf16 v[52:55], v[152:155], v[200:203], v[52:55]
	v_mfma_f32_16x16x32_bf16 v[44:47], v[160:163], v[200:203], v[44:47]
	v_mfma_f32_16x16x32_bf16 v[36:39], v[152:155], v[208:211], v[36:39]
	v_mfma_f32_16x16x32_bf16 v[26:29], v[160:163], v[208:211], v[26:29]
	v_mfma_f32_16x16x32_bf16 v[18:21], v[152:155], v[232:235], v[18:21]
	v_mfma_f32_16x16x32_bf16 v[10:13], v[160:163], v[232:235], v[10:13]
	v_mfma_f32_16x16x32_bf16 v[56:59], v[172:175], v[188:191], v[56:59]
	v_mfma_f32_16x16x32_bf16 v[48:51], v[180:183], v[188:191], v[48:51]
	v_mfma_f32_16x16x32_bf16 v[40:43], v[172:175], v[196:199], v[40:43]
	v_mfma_f32_16x16x32_bf16 v[30:33], v[180:183], v[196:199], v[30:33]
	v_mfma_f32_16x16x32_bf16 v[22:25], v[172:175], v[204:207], v[22:25]
	v_mfma_f32_16x16x32_bf16 v[14:17], v[180:183], v[204:207], v[14:17]
	v_mfma_f32_16x16x32_bf16 v[6:9], v[172:175], v[212:215], v[6:9]
	v_mfma_f32_16x16x32_bf16 v[2:5], v[180:183], v[212:215], v[2:5]
	v_mfma_f32_16x16x32_bf16 v[56:59], v[176:179], v[192:195], v[56:59]
	v_mfma_f32_16x16x32_bf16 v[48:51], v[184:187], v[192:195], v[48:51]
	v_mfma_f32_16x16x32_bf16 v[40:43], v[176:179], v[200:203], v[40:43]
	v_mfma_f32_16x16x32_bf16 v[30:33], v[184:187], v[200:203], v[30:33]
	v_mfma_f32_16x16x32_bf16 v[22:25], v[176:179], v[208:211], v[22:25]
	v_mfma_f32_16x16x32_bf16 v[14:17], v[184:187], v[208:211], v[14:17]
	v_mfma_f32_16x16x32_bf16 v[6:9], v[176:179], v[232:235], v[6:9]
	v_mfma_f32_16x16x32_bf16 v[2:5], v[184:187], v[232:235], v[2:5]
	s_barrier
	s_add_i32 s29, 0, 0x18000
	v_add_u32_e32 v1, s29, v146
	s_add_i32 s30, 0, 0x1c000
	ds_read_b128 v[148:151], v1
	ds_read_b128 v[152:155], v1 offset:1024
	ds_read_b128 v[156:159], v1 offset:2048
	ds_read_b128 v[160:163], v1 offset:3072
	v_add_u32_e32 v1, s30, v146
	ds_read_b128 v[172:175], v1
	ds_read_b128 v[176:179], v1 offset:1024
	ds_read_b128 v[180:183], v1 offset:2048
	ds_read_b128 v[184:187], v1 offset:3072
	s_add_u32 s12, s12, 0x180000
	s_addc_u32 s13, s13, 0
	s_mov_b32 m0, s18
	v_lshl_add_u64 v[240:241], s[12:13], 0, v[132:133]
	ds_read_b128 v[188:191], v147 offset:32768
	ds_read_b128 v[192:195], v147 offset:33792
	ds_read_b128 v[196:199], v147 offset:34816
	ds_read_b128 v[200:203], v147 offset:35840
	ds_read_b128 v[204:207], v147 offset:36864
	ds_read_b128 v[208:211], v147 offset:37888
	ds_read_b128 v[212:215], v147 offset:38912
	ds_read_b128 v[232:235], v147 offset:39936
	global_load_lds_dwordx4 v[240:241], off
	v_lshl_add_u64 v[240:241], s[12:13], 0, v[136:137]
	s_mov_b32 m0, s19
	s_nop 0
	global_load_lds_dwordx4 v[240:241], off
	s_waitcnt vmcnt(8)
	s_waitcnt lgkmcnt(0)
	s_barrier
	s_waitcnt lgkmcnt(0)
	v_mfma_f32_16x16x32_bf16 v[128:131], v[148:151], v[188:191], v[128:131]
	v_mfma_f32_16x16x32_bf16 v[124:127], v[156:159], v[188:191], v[124:127]
	v_mfma_f32_16x16x32_bf16 v[116:119], v[148:151], v[196:199], v[116:119]
	v_mfma_f32_16x16x32_bf16 v[108:111], v[156:159], v[196:199], v[108:111]
	v_mfma_f32_16x16x32_bf16 v[100:103], v[148:151], v[204:207], v[100:103]
	v_mfma_f32_16x16x32_bf16 v[92:95], v[156:159], v[204:207], v[92:95]
	v_mfma_f32_16x16x32_bf16 v[84:87], v[148:151], v[212:215], v[84:87]
	v_mfma_f32_16x16x32_bf16 v[76:79], v[156:159], v[212:215], v[76:79]
	v_mfma_f32_16x16x32_bf16 v[128:131], v[152:155], v[192:195], v[128:131]
	v_mfma_f32_16x16x32_bf16 v[124:127], v[160:163], v[192:195], v[124:127]
	v_mfma_f32_16x16x32_bf16 v[116:119], v[152:155], v[200:203], v[116:119]
	v_mfma_f32_16x16x32_bf16 v[108:111], v[160:163], v[200:203], v[108:111]
	v_mfma_f32_16x16x32_bf16 v[100:103], v[152:155], v[208:211], v[100:103]
	v_mfma_f32_16x16x32_bf16 v[92:95], v[160:163], v[208:211], v[92:95]
	v_mfma_f32_16x16x32_bf16 v[84:87], v[152:155], v[232:235], v[84:87]
	v_mfma_f32_16x16x32_bf16 v[76:79], v[160:163], v[232:235], v[76:79]
	v_mfma_f32_16x16x32_bf16 v[120:123], v[172:175], v[188:191], v[120:123]
	v_mfma_f32_16x16x32_bf16 v[112:115], v[180:183], v[188:191], v[112:115]
	v_mfma_f32_16x16x32_bf16 v[104:107], v[172:175], v[196:199], v[104:107]
	v_mfma_f32_16x16x32_bf16 v[96:99], v[180:183], v[196:199], v[96:99]
	v_mfma_f32_16x16x32_bf16 v[88:91], v[172:175], v[204:207], v[88:91]
	v_mfma_f32_16x16x32_bf16 v[80:83], v[180:183], v[204:207], v[80:83]
	v_mfma_f32_16x16x32_bf16 v[72:75], v[172:175], v[212:215], v[72:75]
	v_mfma_f32_16x16x32_bf16 v[68:71], v[180:183], v[212:215], v[68:71]
	v_mfma_f32_16x16x32_bf16 v[120:123], v[176:179], v[192:195], v[120:123]
	v_mfma_f32_16x16x32_bf16 v[112:115], v[184:187], v[192:195], v[112:115]
	v_mfma_f32_16x16x32_bf16 v[104:107], v[176:179], v[200:203], v[104:107]
	v_mfma_f32_16x16x32_bf16 v[96:99], v[184:187], v[200:203], v[96:99]
	v_mfma_f32_16x16x32_bf16 v[88:91], v[176:179], v[208:211], v[88:91]
	v_mfma_f32_16x16x32_bf16 v[80:83], v[184:187], v[208:211], v[80:83]
	v_mfma_f32_16x16x32_bf16 v[72:75], v[176:179], v[232:235], v[72:75]
	v_mfma_f32_16x16x32_bf16 v[68:71], v[184:187], v[232:235], v[68:71]
	s_barrier
	s_add_i32 s12, s29, s15
	v_lshl_add_u64 v[216:217], v[216:217], 0, s[2:3]
	s_mov_b32 m0, s12
	ds_read_b128 v[188:191], v147 offset:49152
	ds_read_b128 v[192:195], v147 offset:50176
	ds_read_b128 v[196:199], v147 offset:51200
	ds_read_b128 v[200:203], v147 offset:52224
	ds_read_b128 v[204:207], v147 offset:53248
	ds_read_b128 v[208:211], v147 offset:54272
	ds_read_b128 v[212:215], v147 offset:55296
	ds_read_b128 v[232:235], v147 offset:56320
	global_load_lds_dwordx4 v[216:217], off
	s_add_i32 m0, s12, 0x2000
	s_add_u32 s10, s10, 0x180080
	v_lshl_add_u64 v[216:217], v[220:221], 0, s[2:3]
	s_addc_u32 s11, s11, 0
	s_add_i32 s12, s30, s15
	global_load_lds_dwordx4 v[216:217], off
	v_lshl_add_u64 v[216:217], s[10:11], 0, v[134:135]
	s_mov_b32 m0, s12
	s_nop 0
	global_load_lds_dwordx4 v[216:217], off
	v_lshl_add_u64 v[216:217], s[10:11], 0, v[138:139]
	s_add_i32 m0, s12, 0x2000
	s_nop 0
	global_load_lds_dwordx4 v[216:217], off
	v_lshl_add_u64 v[216:217], v[236:237], 0, s[2:3]
	s_mov_b32 m0, s22
	s_nop 0
	global_load_lds_dwordx4 v[216:217], off
	v_lshl_add_u64 v[216:217], v[238:239], 0, s[2:3]
	s_mov_b32 m0, s23
	s_nop 0
	global_load_lds_dwordx4 v[216:217], off
	s_waitcnt vmcnt(8)
	s_waitcnt lgkmcnt(0)
	s_barrier
	s_waitcnt lgkmcnt(0)
	v_mfma_f32_16x16x32_bf16 v[64:67], v[148:151], v[188:191], v[64:67]
	v_mfma_f32_16x16x32_bf16 v[60:63], v[156:159], v[188:191], v[60:63]
	v_mfma_f32_16x16x32_bf16 v[52:55], v[148:151], v[196:199], v[52:55]
	v_mfma_f32_16x16x32_bf16 v[44:47], v[156:159], v[196:199], v[44:47]
	v_mfma_f32_16x16x32_bf16 v[36:39], v[148:151], v[204:207], v[36:39]
	v_mfma_f32_16x16x32_bf16 v[26:29], v[156:159], v[204:207], v[26:29]
	v_mfma_f32_16x16x32_bf16 v[18:21], v[148:151], v[212:215], v[18:21]
	v_mfma_f32_16x16x32_bf16 v[10:13], v[156:159], v[212:215], v[10:13]
	v_mfma_f32_16x16x32_bf16 v[64:67], v[152:155], v[192:195], v[64:67]
	v_mfma_f32_16x16x32_bf16 v[60:63], v[160:163], v[192:195], v[60:63]
	v_mfma_f32_16x16x32_bf16 v[52:55], v[152:155], v[200:203], v[52:55]
	v_mfma_f32_16x16x32_bf16 v[44:47], v[160:163], v[200:203], v[44:47]
	v_mfma_f32_16x16x32_bf16 v[36:39], v[152:155], v[208:211], v[36:39]
	v_mfma_f32_16x16x32_bf16 v[26:29], v[160:163], v[208:211], v[26:29]
	v_mfma_f32_16x16x32_bf16 v[18:21], v[152:155], v[232:235], v[18:21]
	v_mfma_f32_16x16x32_bf16 v[10:13], v[160:163], v[232:235], v[10:13]
	v_mfma_f32_16x16x32_bf16 v[56:59], v[172:175], v[188:191], v[56:59]
	v_mfma_f32_16x16x32_bf16 v[48:51], v[180:183], v[188:191], v[48:51]
	v_mfma_f32_16x16x32_bf16 v[40:43], v[172:175], v[196:199], v[40:43]
	v_mfma_f32_16x16x32_bf16 v[30:33], v[180:183], v[196:199], v[30:33]
	v_mfma_f32_16x16x32_bf16 v[22:25], v[172:175], v[204:207], v[22:25]
	v_mfma_f32_16x16x32_bf16 v[14:17], v[180:183], v[204:207], v[14:17]
	v_mfma_f32_16x16x32_bf16 v[6:9], v[172:175], v[212:215], v[6:9]
	v_mfma_f32_16x16x32_bf16 v[2:5], v[180:183], v[212:215], v[2:5]
	v_mfma_f32_16x16x32_bf16 v[56:59], v[176:179], v[192:195], v[56:59]
	v_mfma_f32_16x16x32_bf16 v[48:51], v[184:187], v[192:195], v[48:51]
	v_mfma_f32_16x16x32_bf16 v[40:43], v[176:179], v[200:203], v[40:43]
	v_mfma_f32_16x16x32_bf16 v[30:33], v[184:187], v[200:203], v[30:33]
	v_mfma_f32_16x16x32_bf16 v[22:25], v[176:179], v[208:211], v[22:25]
	v_mfma_f32_16x16x32_bf16 v[14:17], v[184:187], v[208:211], v[14:17]
	v_mfma_f32_16x16x32_bf16 v[6:9], v[176:179], v[232:235], v[6:9]
	v_mfma_f32_16x16x32_bf16 v[2:5], v[184:187], v[232:235], v[2:5]
	s_barrier
	s_add_i32 s28, s28, 2
	s_add_u32 s8, s8, 0x100
	s_addc_u32 s9, s9, 0
	s_cmp_gt_u32 s28, 29
	s_cbranch_scc0 .LBB0_1446
	s_waitcnt vmcnt(0)
	s_cmpk_lt_u32 s14, 0x100
	s_cbranch_scc0 .LBB0_1449
	s_barrier

.LBB0_1491:
	s_add_u32 s8, s24, s6
	s_addc_u32 s9, s25, s7
	s_add_u32 s8, s8, 0x6a700100
	s_addc_u32 s9, s9, 0
	s_add_u32 s27, s22, s6
	s_addc_u32 s28, s23, s7
	s_add_i32 s29, 0, 0x10000
	s_cmpk_eq_i32 s6, 0x700
	s_cselect_b32 s11, s5, s9
	s_cselect_b32 s10, s4, s8
	v_add_u32_e32 v1, s29, v145
	s_cselect_b32 s9, s1, s28
	s_cselect_b32 s8, s0, s27
	s_add_i32 s27, 0, 0x14000
	ds_read_b128 v[148:151], v1
	ds_read_b128 v[152:155], v1 offset:1024
	ds_read_b128 v[156:159], v1 offset:2048
	ds_read_b128 v[160:163], v1 offset:3072
	v_add_u32_e32 v1, s27, v145
	ds_read_b128 v[172:175], v1
	ds_read_b128 v[176:179], v1 offset:1024
	ds_read_b128 v[180:183], v1 offset:2048
	ds_read_b128 v[184:187], v1 offset:3072
	v_lshl_add_u64 v[216:217], v[142:143], 0, s[6:7]
	s_add_i32 m0, s14, 0xc000
	ds_read_b128 v[188:191], v146
	ds_read_b128 v[192:195], v146 offset:1024
	ds_read_b128 v[196:199], v146 offset:2048
	ds_read_b128 v[200:203], v146 offset:3072
	ds_read_b128 v[204:207], v146 offset:4096
	ds_read_b128 v[208:211], v146 offset:5120
	ds_read_b128 v[212:215], v146 offset:6144
	ds_read_b128 v[232:235], v146 offset:7168
	global_load_lds_dwordx4 v[216:217], off
	v_lshl_add_u64 v[216:217], v[140:141], 0, s[6:7]
	s_add_i32 m0, s14, 0xe000
	s_nop 0
	global_load_lds_dwordx4 v[216:217], off
	s_waitcnt vmcnt(8)
	s_waitcnt lgkmcnt(0)
	s_barrier
	s_waitcnt lgkmcnt(0)
	v_mfma_f32_16x16x32_bf16 v[128:131], v[148:151], v[188:191], v[128:131]
	v_mfma_f32_16x16x32_bf16 v[124:127], v[156:159], v[188:191], v[124:127]
	v_mfma_f32_16x16x32_bf16 v[120:123], v[148:151], v[196:199], v[120:123]
	v_mfma_f32_16x16x32_bf16 v[116:119], v[156:159], v[196:199], v[116:119]
	v_mfma_f32_16x16x32_bf16 v[108:111], v[148:151], v[204:207], v[108:111]
	v_mfma_f32_16x16x32_bf16 v[100:103], v[156:159], v[204:207], v[100:103]
	v_mfma_f32_16x16x32_bf16 v[92:95], v[148:151], v[212:215], v[92:95]
	v_mfma_f32_16x16x32_bf16 v[84:87], v[156:159], v[212:215], v[84:87]
	v_mfma_f32_16x16x32_bf16 v[128:131], v[152:155], v[192:195], v[128:131]
	v_mfma_f32_16x16x32_bf16 v[124:127], v[160:163], v[192:195], v[124:127]
	v_mfma_f32_16x16x32_bf16 v[120:123], v[152:155], v[200:203], v[120:123]
	v_mfma_f32_16x16x32_bf16 v[116:119], v[160:163], v[200:203], v[116:119]
	v_mfma_f32_16x16x32_bf16 v[108:111], v[152:155], v[208:211], v[108:111]
	v_mfma_f32_16x16x32_bf16 v[100:103], v[160:163], v[208:211], v[100:103]
	v_mfma_f32_16x16x32_bf16 v[92:95], v[152:155], v[232:235], v[92:95]
	v_mfma_f32_16x16x32_bf16 v[84:87], v[160:163], v[232:235], v[84:87]
	v_mfma_f32_16x16x32_bf16 v[112:115], v[172:175], v[188:191], v[112:115]
	v_mfma_f32_16x16x32_bf16 v[104:107], v[180:183], v[188:191], v[104:107]
	v_mfma_f32_16x16x32_bf16 v[96:99], v[172:175], v[196:199], v[96:99]
	v_mfma_f32_16x16x32_bf16 v[88:91], v[180:183], v[196:199], v[88:91]
	v_mfma_f32_16x16x32_bf16 v[80:83], v[172:175], v[204:207], v[80:83]
	v_mfma_f32_16x16x32_bf16 v[76:79], v[180:183], v[204:207], v[76:79]
	v_mfma_f32_16x16x32_bf16 v[72:75], v[172:175], v[212:215], v[72:75]
	v_mfma_f32_16x16x32_bf16 v[68:71], v[180:183], v[212:215], v[68:71]
	v_mfma_f32_16x16x32_bf16 v[112:115], v[176:179], v[192:195], v[112:115]
	v_mfma_f32_16x16x32_bf16 v[104:107], v[184:187], v[192:195], v[104:107]
	v_mfma_f32_16x16x32_bf16 v[96:99], v[176:179], v[200:203], v[96:99]
	v_mfma_f32_16x16x32_bf16 v[88:91], v[184:187], v[200:203], v[88:91]
	v_mfma_f32_16x16x32_bf16 v[80:83], v[176:179], v[208:211], v[80:83]
	v_mfma_f32_16x16x32_bf16 v[76:79], v[184:187], v[208:211], v[76:79]
	v_mfma_f32_16x16x32_bf16 v[72:75], v[176:179], v[232:235], v[72:75]
	v_mfma_f32_16x16x32_bf16 v[68:71], v[184:187], v[232:235], v[68:71]
	s_barrier
	s_add_i32 s28, s29, s13
	v_lshl_add_u64 v[216:217], s[8:9], 0, v[134:135]
	s_mov_b32 m0, s28
	ds_read_b128 v[188:191], v146 offset:16384
	ds_read_b128 v[192:195], v146 offset:17408
	ds_read_b128 v[196:199], v146 offset:18432
	ds_read_b128 v[200:203], v146 offset:19456
	ds_read_b128 v[204:207], v146 offset:20480
	ds_read_b128 v[208:211], v146 offset:21504
	ds_read_b128 v[212:215], v146 offset:22528
	ds_read_b128 v[232:235], v146 offset:23552
	global_load_lds_dwordx4 v[216:217], off
	s_add_i32 m0, s28, 0x2000
	s_add_u32 s28, s8, 0x100000
	v_lshl_add_u64 v[220:221], s[8:9], 0, v[138:139]
	s_addc_u32 s29, s9, 0
	s_add_i32 s27, s27, s13
	global_load_lds_dwordx4 v[220:221], off
	v_lshl_add_u64 v[236:237], s[28:29], 0, v[134:135]
	s_mov_b32 m0, s27
	v_lshl_add_u64 v[238:239], s[10:11], 0, v[136:137]
	global_load_lds_dwordx4 v[236:237], off
	v_lshl_add_u64 v[236:237], s[28:29], 0, v[138:139]
	s_add_i32 m0, s27, 0x2000
	s_nop 0
	global_load_lds_dwordx4 v[236:237], off
	v_lshl_add_u64 v[236:237], s[10:11], 0, v[132:133]
	s_mov_b32 m0, s14
	s_nop 0
	global_load_lds_dwordx4 v[236:237], off
	s_mov_b32 m0, s15
	s_nop 0
	global_load_lds_dwordx4 v[238:239], off
	s_waitcnt vmcnt(8)
	s_waitcnt lgkmcnt(0)
	s_barrier
	s_waitcnt lgkmcnt(0)
	v_mfma_f32_16x16x32_bf16 v[64:67], v[148:151], v[188:191], v[64:67]
	v_mfma_f32_16x16x32_bf16 v[60:63], v[156:159], v[188:191], v[60:63]
	v_mfma_f32_16x16x32_bf16 v[56:59], v[148:151], v[196:199], v[56:59]
	v_mfma_f32_16x16x32_bf16 v[52:55], v[156:159], v[196:199], v[52:55]
	v_mfma_f32_16x16x32_bf16 v[40:43], v[148:151], v[204:207], v[40:43]
	v_mfma_f32_16x16x32_bf16 v[36:39], v[156:159], v[204:207], v[36:39]
	v_mfma_f32_16x16x32_bf16 v[22:25], v[148:151], v[212:215], v[22:25]
	v_mfma_f32_16x16x32_bf16 v[18:21], v[156:159], v[212:215], v[18:21]
	v_mfma_f32_16x16x32_bf16 v[64:67], v[152:155], v[192:195], v[64:67]
	v_mfma_f32_16x16x32_bf16 v[60:63], v[160:163], v[192:195], v[60:63]
	v_mfma_f32_16x16x32_bf16 v[56:59], v[152:155], v[200:203], v[56:59]
	v_mfma_f32_16x16x32_bf16 v[52:55], v[160:163], v[200:203], v[52:55]
	v_mfma_f32_16x16x32_bf16 v[40:43], v[152:155], v[208:211], v[40:43]
	v_mfma_f32_16x16x32_bf16 v[36:39], v[160:163], v[208:211], v[36:39]
	v_mfma_f32_16x16x32_bf16 v[22:25], v[152:155], v[232:235], v[22:25]
	v_mfma_f32_16x16x32_bf16 v[18:21], v[160:163], v[232:235], v[18:21]
	v_mfma_f32_16x16x32_bf16 v[48:51], v[172:175], v[188:191], v[48:51]
	v_mfma_f32_16x16x32_bf16 v[44:47], v[180:183], v[188:191], v[44:47]
	v_mfma_f32_16x16x32_bf16 v[30:33], v[172:175], v[196:199], v[30:33]
	v_mfma_f32_16x16x32_bf16 v[26:29], v[180:183], v[196:199], v[26:29]
	v_mfma_f32_16x16x32_bf16 v[14:17], v[172:175], v[204:207], v[14:17]
	v_mfma_f32_16x16x32_bf16 v[10:13], v[180:183], v[204:207], v[10:13]
	v_mfma_f32_16x16x32_bf16 v[6:9], v[172:175], v[212:215], v[6:9]
	v_mfma_f32_16x16x32_bf16 v[2:5], v[180:183], v[212:215], v[2:5]
	v_mfma_f32_16x16x32_bf16 v[48:51], v[176:179], v[192:195], v[48:51]
	v_mfma_f32_16x16x32_bf16 v[44:47], v[184:187], v[192:195], v[44:47]
	v_mfma_f32_16x16x32_bf16 v[30:33], v[176:179], v[200:203], v[30:33]
	v_mfma_f32_16x16x32_bf16 v[26:29], v[184:187], v[200:203], v[26:29]
	v_mfma_f32_16x16x32_bf16 v[14:17], v[176:179], v[208:211], v[14:17]
	v_mfma_f32_16x16x32_bf16 v[10:13], v[184:187], v[208:211], v[10:13]
	v_mfma_f32_16x16x32_bf16 v[6:9], v[176:179], v[232:235], v[6:9]
	v_mfma_f32_16x16x32_bf16 v[2:5], v[184:187], v[232:235], v[2:5]
	s_barrier
	s_add_i32 s27, 0, 0x18000
	v_add_u32_e32 v1, s27, v145
	s_add_i32 s28, 0, 0x1c000
	ds_read_b128 v[148:151], v1
	ds_read_b128 v[152:155], v1 offset:1024
	ds_read_b128 v[156:159], v1 offset:2048
	ds_read_b128 v[160:163], v1 offset:3072
	v_add_u32_e32 v1, s28, v145
	ds_read_b128 v[172:175], v1
	ds_read_b128 v[176:179], v1 offset:1024
	ds_read_b128 v[180:183], v1 offset:2048
	ds_read_b128 v[184:187], v1 offset:3072
	s_add_u32 s10, s10, 0x100000
	s_addc_u32 s11, s11, 0
	s_mov_b32 m0, s16
	v_lshl_add_u64 v[240:241], s[10:11], 0, v[132:133]
	ds_read_b128 v[188:191], v146 offset:32768
	ds_read_b128 v[192:195], v146 offset:33792
	ds_read_b128 v[196:199], v146 offset:34816
	ds_read_b128 v[200:203], v146 offset:35840
	ds_read_b128 v[204:207], v146 offset:36864
	ds_read_b128 v[208:211], v146 offset:37888
	ds_read_b128 v[212:215], v146 offset:38912
	ds_read_b128 v[232:235], v146 offset:39936
	global_load_lds_dwordx4 v[240:241], off
	v_lshl_add_u64 v[240:241], s[10:11], 0, v[136:137]
	s_mov_b32 m0, s17
	s_nop 0
	global_load_lds_dwordx4 v[240:241], off
	s_waitcnt vmcnt(8)
	s_waitcnt lgkmcnt(0)
	s_barrier
	s_waitcnt lgkmcnt(0)
	v_mfma_f32_16x16x32_bf16 v[128:131], v[148:151], v[188:191], v[128:131]
	v_mfma_f32_16x16x32_bf16 v[124:127], v[156:159], v[188:191], v[124:127]
	v_mfma_f32_16x16x32_bf16 v[120:123], v[148:151], v[196:199], v[120:123]
	v_mfma_f32_16x16x32_bf16 v[116:119], v[156:159], v[196:199], v[116:119]
	v_mfma_f32_16x16x32_bf16 v[108:111], v[148:151], v[204:207], v[108:111]
	v_mfma_f32_16x16x32_bf16 v[100:103], v[156:159], v[204:207], v[100:103]
	v_mfma_f32_16x16x32_bf16 v[92:95], v[148:151], v[212:215], v[92:95]
	v_mfma_f32_16x16x32_bf16 v[84:87], v[156:159], v[212:215], v[84:87]
	v_mfma_f32_16x16x32_bf16 v[128:131], v[152:155], v[192:195], v[128:131]
	v_mfma_f32_16x16x32_bf16 v[124:127], v[160:163], v[192:195], v[124:127]
	v_mfma_f32_16x16x32_bf16 v[120:123], v[152:155], v[200:203], v[120:123]
	v_mfma_f32_16x16x32_bf16 v[116:119], v[160:163], v[200:203], v[116:119]
	v_mfma_f32_16x16x32_bf16 v[108:111], v[152:155], v[208:211], v[108:111]
	v_mfma_f32_16x16x32_bf16 v[100:103], v[160:163], v[208:211], v[100:103]
	v_mfma_f32_16x16x32_bf16 v[92:95], v[152:155], v[232:235], v[92:95]
	v_mfma_f32_16x16x32_bf16 v[84:87], v[160:163], v[232:235], v[84:87]
	v_mfma_f32_16x16x32_bf16 v[112:115], v[172:175], v[188:191], v[112:115]
	v_mfma_f32_16x16x32_bf16 v[104:107], v[180:183], v[188:191], v[104:107]
	v_mfma_f32_16x16x32_bf16 v[96:99], v[172:175], v[196:199], v[96:99]
	v_mfma_f32_16x16x32_bf16 v[88:91], v[180:183], v[196:199], v[88:91]
	v_mfma_f32_16x16x32_bf16 v[80:83], v[172:175], v[204:207], v[80:83]
	v_mfma_f32_16x16x32_bf16 v[76:79], v[180:183], v[204:207], v[76:79]
	v_mfma_f32_16x16x32_bf16 v[72:75], v[172:175], v[212:215], v[72:75]
	v_mfma_f32_16x16x32_bf16 v[68:71], v[180:183], v[212:215], v[68:71]
	v_mfma_f32_16x16x32_bf16 v[112:115], v[176:179], v[192:195], v[112:115]
	v_mfma_f32_16x16x32_bf16 v[104:107], v[184:187], v[192:195], v[104:107]
	v_mfma_f32_16x16x32_bf16 v[96:99], v[176:179], v[200:203], v[96:99]
	v_mfma_f32_16x16x32_bf16 v[88:91], v[184:187], v[200:203], v[88:91]
	v_mfma_f32_16x16x32_bf16 v[80:83], v[176:179], v[208:211], v[80:83]
	v_mfma_f32_16x16x32_bf16 v[76:79], v[184:187], v[208:211], v[76:79]
	v_mfma_f32_16x16x32_bf16 v[72:75], v[176:179], v[232:235], v[72:75]
	v_mfma_f32_16x16x32_bf16 v[68:71], v[184:187], v[232:235], v[68:71]
	s_barrier
	s_add_i32 s10, s27, s13
	v_lshl_add_u64 v[216:217], v[216:217], 0, s[2:3]
	s_mov_b32 m0, s10
	ds_read_b128 v[188:191], v146 offset:49152
	ds_read_b128 v[192:195], v146 offset:50176
	ds_read_b128 v[196:199], v146 offset:51200
	ds_read_b128 v[200:203], v146 offset:52224
	ds_read_b128 v[204:207], v146 offset:53248
	ds_read_b128 v[208:211], v146 offset:54272
	ds_read_b128 v[212:215], v146 offset:55296
	ds_read_b128 v[232:235], v146 offset:56320
	global_load_lds_dwordx4 v[216:217], off
	s_add_i32 m0, s10, 0x2000
	s_add_u32 s8, s8, 0x100080
	v_lshl_add_u64 v[216:217], v[220:221], 0, s[2:3]
	s_addc_u32 s9, s9, 0
	s_add_i32 s10, s28, s13
	global_load_lds_dwordx4 v[216:217], off
	v_lshl_add_u64 v[216:217], s[8:9], 0, v[134:135]
	s_mov_b32 m0, s10
	s_nop 0
	global_load_lds_dwordx4 v[216:217], off
	v_lshl_add_u64 v[216:217], s[8:9], 0, v[138:139]
	s_add_i32 m0, s10, 0x2000
	s_nop 0
	global_load_lds_dwordx4 v[216:217], off
	v_lshl_add_u64 v[216:217], v[236:237], 0, s[2:3]
	s_mov_b32 m0, s20
	s_nop 0
	global_load_lds_dwordx4 v[216:217], off
	v_lshl_add_u64 v[216:217], v[238:239], 0, s[2:3]
	s_mov_b32 m0, s21
	s_nop 0
	global_load_lds_dwordx4 v[216:217], off
	s_waitcnt vmcnt(8)
	s_waitcnt lgkmcnt(0)
	s_barrier
	s_waitcnt lgkmcnt(0)
	v_mfma_f32_16x16x32_bf16 v[64:67], v[148:151], v[188:191], v[64:67]
	v_mfma_f32_16x16x32_bf16 v[60:63], v[156:159], v[188:191], v[60:63]
	v_mfma_f32_16x16x32_bf16 v[56:59], v[148:151], v[196:199], v[56:59]
	v_mfma_f32_16x16x32_bf16 v[52:55], v[156:159], v[196:199], v[52:55]
	v_mfma_f32_16x16x32_bf16 v[40:43], v[148:151], v[204:207], v[40:43]
	v_mfma_f32_16x16x32_bf16 v[36:39], v[156:159], v[204:207], v[36:39]
	v_mfma_f32_16x16x32_bf16 v[22:25], v[148:151], v[212:215], v[22:25]
	v_mfma_f32_16x16x32_bf16 v[18:21], v[156:159], v[212:215], v[18:21]
	v_mfma_f32_16x16x32_bf16 v[64:67], v[152:155], v[192:195], v[64:67]
	v_mfma_f32_16x16x32_bf16 v[60:63], v[160:163], v[192:195], v[60:63]
	v_mfma_f32_16x16x32_bf16 v[56:59], v[152:155], v[200:203], v[56:59]
	v_mfma_f32_16x16x32_bf16 v[52:55], v[160:163], v[200:203], v[52:55]
	v_mfma_f32_16x16x32_bf16 v[40:43], v[152:155], v[208:211], v[40:43]
	v_mfma_f32_16x16x32_bf16 v[36:39], v[160:163], v[208:211], v[36:39]
	v_mfma_f32_16x16x32_bf16 v[22:25], v[152:155], v[232:235], v[22:25]
	v_mfma_f32_16x16x32_bf16 v[18:21], v[160:163], v[232:235], v[18:21]
	v_mfma_f32_16x16x32_bf16 v[48:51], v[172:175], v[188:191], v[48:51]
	v_mfma_f32_16x16x32_bf16 v[44:47], v[180:183], v[188:191], v[44:47]
	v_mfma_f32_16x16x32_bf16 v[30:33], v[172:175], v[196:199], v[30:33]
	v_mfma_f32_16x16x32_bf16 v[26:29], v[180:183], v[196:199], v[26:29]
	v_mfma_f32_16x16x32_bf16 v[14:17], v[172:175], v[204:207], v[14:17]
	v_mfma_f32_16x16x32_bf16 v[10:13], v[180:183], v[204:207], v[10:13]
	v_mfma_f32_16x16x32_bf16 v[6:9], v[172:175], v[212:215], v[6:9]
	v_mfma_f32_16x16x32_bf16 v[2:5], v[180:183], v[212:215], v[2:5]
	v_mfma_f32_16x16x32_bf16 v[48:51], v[176:179], v[192:195], v[48:51]
	v_mfma_f32_16x16x32_bf16 v[44:47], v[184:187], v[192:195], v[44:47]
	v_mfma_f32_16x16x32_bf16 v[30:33], v[176:179], v[200:203], v[30:33]
	v_mfma_f32_16x16x32_bf16 v[26:29], v[184:187], v[200:203], v[26:29]
	v_mfma_f32_16x16x32_bf16 v[14:17], v[176:179], v[208:211], v[14:17]
	v_mfma_f32_16x16x32_bf16 v[10:13], v[184:187], v[208:211], v[10:13]
	v_mfma_f32_16x16x32_bf16 v[6:9], v[176:179], v[232:235], v[6:9]
	v_mfma_f32_16x16x32_bf16 v[2:5], v[184:187], v[232:235], v[2:5]
	s_barrier
	s_add_i32 s26, s26, 2
	s_add_u32 s6, s6, 0x100
	s_addc_u32 s7, s7, 0
	s_cmp_gt_u32 s26, 13
	s_cbranch_scc0 .LBB0_1491
	s_waitcnt vmcnt(0)
	s_cmpk_lt_u32 s12, 0x100
	s_cbranch_scc0 .LBB0_1494
	s_barrier

.LBB0_1624:
	s_add_u32 s20, s18, 0x100
	s_addc_u32 s21, s19, 0
	s_add_i32 s50, 0, 0x10000
	s_cmp_eq_u32 s41, 28
	s_cselect_b32 s25, s15, s21
	s_cselect_b32 s24, s14, s20
	v_add_u32_e32 v1, s50, v184
	s_cselect_b32 s23, s17, s40
	s_cselect_b32 s22, s16, s13
	s_add_i32 s51, 0, 0x14000
	s_waitcnt lgkmcnt(0)
	ds_read_b128 v[134:137], v1
	ds_read_b128 v[138:141], v1 offset:1024
	ds_read_b128 v[142:145], v1 offset:2048
	ds_read_b128 v[146:149], v1 offset:3072
	v_add_u32_e32 v1, s51, v184
	ds_read_b128 v[150:153], v1
	ds_read_b128 v[154:157], v1 offset:1024
	ds_read_b128 v[158:161], v1 offset:2048
	ds_read_b128 v[186:189], v1 offset:3072
	v_lshl_add_u64 v[36:37], s[18:19], 0, v[180:181]
	s_add_i32 m0, s29, 0xc000
	ds_read_b128 v[190:193], v185
	ds_read_b128 v[194:197], v185 offset:1024
	ds_read_b128 v[198:201], v185 offset:2048
	ds_read_b128 v[202:205], v185 offset:3072
	ds_read_b128 v[206:209], v185 offset:4096
	ds_read_b128 v[210:213], v185 offset:5120
	ds_read_b128 v[214:217], v185 offset:6144
	ds_read_b128 v[232:235], v185 offset:7168
	global_load_lds_dwordx4 v[36:37], off
	v_lshl_add_u64 v[36:37], s[18:19], 0, v[178:179]
	s_add_i32 m0, s29, 0xe000
	s_nop 0
	global_load_lds_dwordx4 v[36:37], off
	s_waitcnt vmcnt(8)
	s_waitcnt lgkmcnt(0)
	s_barrier
	s_waitcnt lgkmcnt(0)
	v_mfma_f32_16x16x32_bf16 v[130:133], v[134:137], v[190:193], v[130:133]
	v_mfma_f32_16x16x32_bf16 v[126:129], v[142:145], v[190:193], v[126:129]
	v_mfma_f32_16x16x32_bf16 v[122:125], v[134:137], v[198:201], v[122:125]
	v_mfma_f32_16x16x32_bf16 v[118:121], v[142:145], v[198:201], v[118:121]
	v_mfma_f32_16x16x32_bf16 v[114:117], v[134:137], v[206:209], v[114:117]
	v_mfma_f32_16x16x32_bf16 v[110:113], v[142:145], v[206:209], v[110:113]
	v_mfma_f32_16x16x32_bf16 v[106:109], v[134:137], v[214:217], v[106:109]
	v_mfma_f32_16x16x32_bf16 v[102:105], v[142:145], v[214:217], v[102:105]
	v_mfma_f32_16x16x32_bf16 v[130:133], v[138:141], v[194:197], v[130:133]
	v_mfma_f32_16x16x32_bf16 v[126:129], v[146:149], v[194:197], v[126:129]
	v_mfma_f32_16x16x32_bf16 v[122:125], v[138:141], v[202:205], v[122:125]
	v_mfma_f32_16x16x32_bf16 v[118:121], v[146:149], v[202:205], v[118:121]
	v_mfma_f32_16x16x32_bf16 v[114:117], v[138:141], v[210:213], v[114:117]
	v_mfma_f32_16x16x32_bf16 v[110:113], v[146:149], v[210:213], v[110:113]
	v_mfma_f32_16x16x32_bf16 v[106:109], v[138:141], v[232:235], v[106:109]
	v_mfma_f32_16x16x32_bf16 v[102:105], v[146:149], v[232:235], v[102:105]
	v_mfma_f32_16x16x32_bf16 v[98:101], v[150:153], v[190:193], v[98:101]
	v_mfma_f32_16x16x32_bf16 v[94:97], v[158:161], v[190:193], v[94:97]
	v_mfma_f32_16x16x32_bf16 v[90:93], v[150:153], v[198:201], v[90:93]
	v_mfma_f32_16x16x32_bf16 v[86:89], v[158:161], v[198:201], v[86:89]
	v_mfma_f32_16x16x32_bf16 v[82:85], v[150:153], v[206:209], v[82:85]
	v_mfma_f32_16x16x32_bf16 v[78:81], v[158:161], v[206:209], v[78:81]
	v_mfma_f32_16x16x32_bf16 v[74:77], v[150:153], v[214:217], v[74:77]
	v_mfma_f32_16x16x32_bf16 v[70:73], v[158:161], v[214:217], v[70:73]
	v_mfma_f32_16x16x32_bf16 v[98:101], v[154:157], v[194:197], v[98:101]
	v_mfma_f32_16x16x32_bf16 v[94:97], v[186:189], v[194:197], v[94:97]
	v_mfma_f32_16x16x32_bf16 v[90:93], v[154:157], v[202:205], v[90:93]
	v_mfma_f32_16x16x32_bf16 v[86:89], v[186:189], v[202:205], v[86:89]
	v_mfma_f32_16x16x32_bf16 v[82:85], v[154:157], v[210:213], v[82:85]
	v_mfma_f32_16x16x32_bf16 v[78:81], v[186:189], v[210:213], v[78:81]
	v_mfma_f32_16x16x32_bf16 v[74:77], v[154:157], v[232:235], v[74:77]
	v_mfma_f32_16x16x32_bf16 v[70:73], v[186:189], v[232:235], v[70:73]
	s_barrier
	s_add_i32 s18, s50, s28
	v_lshl_add_u64 v[220:221], s[22:23], 0, v[174:175]
	s_mov_b32 m0, s18
	ds_read_b128 v[190:193], v185 offset:16384
	ds_read_b128 v[194:197], v185 offset:17408
	ds_read_b128 v[198:201], v185 offset:18432
	ds_read_b128 v[202:205], v185 offset:19456
	ds_read_b128 v[206:209], v185 offset:20480
	ds_read_b128 v[210:213], v185 offset:21504
	ds_read_b128 v[214:217], v185 offset:22528
	ds_read_b128 v[232:235], v185 offset:23552
	global_load_lds_dwordx4 v[220:221], off
	s_add_i32 m0, s18, 0x2000
	s_add_u32 s18, s22, 0x180000
	v_lshl_add_u64 v[236:237], s[22:23], 0, v[162:163]
	s_addc_u32 s19, s23, 0
	s_add_i32 s50, s51, s28
	global_load_lds_dwordx4 v[236:237], off
	v_lshl_add_u64 v[36:37], s[18:19], 0, v[174:175]
	s_mov_b32 m0, s50
	v_lshl_add_u64 v[238:239], s[24:25], 0, v[176:177]
	global_load_lds_dwordx4 v[36:37], off
	v_lshl_add_u64 v[36:37], s[18:19], 0, v[162:163]
	s_add_i32 m0, s50, 0x2000
	v_lshl_add_u64 v[240:241], s[24:25], 0, v[172:173]
	global_load_lds_dwordx4 v[36:37], off
	s_mov_b32 m0, s29
	s_nop 0
	global_load_lds_dwordx4 v[238:239], off
	s_mov_b32 m0, s30
	s_nop 0
	global_load_lds_dwordx4 v[240:241], off
	s_waitcnt vmcnt(8)
	s_waitcnt lgkmcnt(0)
	s_barrier
	s_waitcnt lgkmcnt(0)
	v_mfma_f32_16x16x32_bf16 v[66:69], v[134:137], v[190:193], v[66:69]
	v_mfma_f32_16x16x32_bf16 v[62:65], v[142:145], v[190:193], v[62:65]
	v_mfma_f32_16x16x32_bf16 v[58:61], v[134:137], v[198:201], v[58:61]
	v_mfma_f32_16x16x32_bf16 v[54:57], v[142:145], v[198:201], v[54:57]
	v_mfma_f32_16x16x32_bf16 v[50:53], v[134:137], v[206:209], v[50:53]
	v_mfma_f32_16x16x32_bf16 v[46:49], v[142:145], v[206:209], v[46:49]
	v_mfma_f32_16x16x32_bf16 v[42:45], v[134:137], v[214:217], v[42:45]
	v_mfma_f32_16x16x32_bf16 v[36:39], v[142:145], v[214:217], v[38:41]
	v_mfma_f32_16x16x32_bf16 v[66:69], v[138:141], v[194:197], v[66:69]
	v_mfma_f32_16x16x32_bf16 v[62:65], v[146:149], v[194:197], v[62:65]
	v_mfma_f32_16x16x32_bf16 v[58:61], v[138:141], v[202:205], v[58:61]
	v_mfma_f32_16x16x32_bf16 v[54:57], v[146:149], v[202:205], v[54:57]
	v_mfma_f32_16x16x32_bf16 v[50:53], v[138:141], v[210:213], v[50:53]
	v_mfma_f32_16x16x32_bf16 v[46:49], v[146:149], v[210:213], v[46:49]
	v_mfma_f32_16x16x32_bf16 v[42:45], v[138:141], v[232:235], v[42:45]
	v_mfma_f32_16x16x32_bf16 v[36:39], v[146:149], v[232:235], v[36:39]
	v_mfma_f32_16x16x32_bf16 v[30:33], v[150:153], v[190:193], v[30:33]
	v_mfma_f32_16x16x32_bf16 v[26:29], v[158:161], v[190:193], v[26:29]
	v_mfma_f32_16x16x32_bf16 v[22:25], v[150:153], v[198:201], v[22:25]
	v_mfma_f32_16x16x32_bf16 v[18:21], v[158:161], v[198:201], v[18:21]
	v_mfma_f32_16x16x32_bf16 v[14:17], v[150:153], v[206:209], v[14:17]
	v_mfma_f32_16x16x32_bf16 v[10:13], v[158:161], v[206:209], v[10:13]
	v_mfma_f32_16x16x32_bf16 v[6:9], v[150:153], v[214:217], v[6:9]
	v_mfma_f32_16x16x32_bf16 v[2:5], v[158:161], v[214:217], v[2:5]
	v_mfma_f32_16x16x32_bf16 v[30:33], v[154:157], v[194:197], v[30:33]
	v_mfma_f32_16x16x32_bf16 v[26:29], v[186:189], v[194:197], v[26:29]
	v_mfma_f32_16x16x32_bf16 v[22:25], v[154:157], v[202:205], v[22:25]
	v_mfma_f32_16x16x32_bf16 v[18:21], v[186:189], v[202:205], v[18:21]
	v_mfma_f32_16x16x32_bf16 v[14:17], v[154:157], v[210:213], v[14:17]
	v_mfma_f32_16x16x32_bf16 v[10:13], v[186:189], v[210:213], v[10:13]
	v_mfma_f32_16x16x32_bf16 v[6:9], v[154:157], v[232:235], v[6:9]
	v_mfma_f32_16x16x32_bf16 v[2:5], v[186:189], v[232:235], v[2:5]
	s_barrier
	s_add_i32 s50, 0, 0x18000
	v_add_u32_e32 v1, s50, v184
	s_add_i32 s51, 0, 0x1c000
	ds_read_b128 v[134:137], v1
	ds_read_b128 v[138:141], v1 offset:1024
	ds_read_b128 v[142:145], v1 offset:2048
	ds_read_b128 v[146:149], v1 offset:3072
	v_add_u32_e32 v1, s51, v184
	ds_read_b128 v[150:153], v1
	ds_read_b128 v[154:157], v1 offset:1024
	ds_read_b128 v[158:161], v1 offset:2048
	ds_read_b128 v[186:189], v1 offset:3072
	s_add_u32 s18, s24, 0x180000
	s_addc_u32 s19, s25, 0
	s_mov_b32 m0, s31
	v_lshl_add_u64 v[40:41], s[18:19], 0, v[176:177]
	ds_read_b128 v[190:193], v185 offset:32768
	ds_read_b128 v[194:197], v185 offset:33792
	ds_read_b128 v[198:201], v185 offset:34816
	ds_read_b128 v[202:205], v185 offset:35840
	ds_read_b128 v[206:209], v185 offset:36864
	ds_read_b128 v[210:213], v185 offset:37888
	ds_read_b128 v[214:217], v185 offset:38912
	ds_read_b128 v[232:235], v185 offset:39936
	global_load_lds_dwordx4 v[40:41], off
	v_lshl_add_u64 v[40:41], s[18:19], 0, v[172:173]
	s_mov_b32 m0, s34
	s_nop 0
	global_load_lds_dwordx4 v[40:41], off
	s_waitcnt vmcnt(8)
	s_waitcnt lgkmcnt(0)
	s_barrier
	s_waitcnt lgkmcnt(0)
	v_mfma_f32_16x16x32_bf16 v[130:133], v[134:137], v[190:193], v[130:133]
	v_mfma_f32_16x16x32_bf16 v[126:129], v[142:145], v[190:193], v[126:129]
	v_mfma_f32_16x16x32_bf16 v[122:125], v[134:137], v[198:201], v[122:125]
	v_mfma_f32_16x16x32_bf16 v[118:121], v[142:145], v[198:201], v[118:121]
	v_mfma_f32_16x16x32_bf16 v[114:117], v[134:137], v[206:209], v[114:117]
	v_mfma_f32_16x16x32_bf16 v[110:113], v[142:145], v[206:209], v[110:113]
	v_mfma_f32_16x16x32_bf16 v[106:109], v[134:137], v[214:217], v[106:109]
	v_mfma_f32_16x16x32_bf16 v[102:105], v[142:145], v[214:217], v[102:105]
	v_mfma_f32_16x16x32_bf16 v[130:133], v[138:141], v[194:197], v[130:133]
	v_mfma_f32_16x16x32_bf16 v[126:129], v[146:149], v[194:197], v[126:129]
	v_mfma_f32_16x16x32_bf16 v[122:125], v[138:141], v[202:205], v[122:125]
	v_mfma_f32_16x16x32_bf16 v[118:121], v[146:149], v[202:205], v[118:121]
	v_mfma_f32_16x16x32_bf16 v[114:117], v[138:141], v[210:213], v[114:117]
	v_mfma_f32_16x16x32_bf16 v[110:113], v[146:149], v[210:213], v[110:113]
	v_mfma_f32_16x16x32_bf16 v[106:109], v[138:141], v[232:235], v[106:109]
	v_mfma_f32_16x16x32_bf16 v[102:105], v[146:149], v[232:235], v[102:105]
	v_mfma_f32_16x16x32_bf16 v[98:101], v[150:153], v[190:193], v[98:101]
	v_mfma_f32_16x16x32_bf16 v[94:97], v[158:161], v[190:193], v[94:97]
	v_mfma_f32_16x16x32_bf16 v[90:93], v[150:153], v[198:201], v[90:93]
	v_mfma_f32_16x16x32_bf16 v[86:89], v[158:161], v[198:201], v[86:89]
	v_mfma_f32_16x16x32_bf16 v[82:85], v[150:153], v[206:209], v[82:85]
	v_mfma_f32_16x16x32_bf16 v[78:81], v[158:161], v[206:209], v[78:81]
	v_mfma_f32_16x16x32_bf16 v[74:77], v[150:153], v[214:217], v[74:77]
	v_mfma_f32_16x16x32_bf16 v[70:73], v[158:161], v[214:217], v[70:73]
	v_mfma_f32_16x16x32_bf16 v[98:101], v[154:157], v[194:197], v[98:101]
	v_mfma_f32_16x16x32_bf16 v[94:97], v[186:189], v[194:197], v[94:97]
	v_mfma_f32_16x16x32_bf16 v[90:93], v[154:157], v[202:205], v[90:93]
	v_mfma_f32_16x16x32_bf16 v[86:89], v[186:189], v[202:205], v[86:89]
	v_mfma_f32_16x16x32_bf16 v[82:85], v[154:157], v[210:213], v[82:85]
	v_mfma_f32_16x16x32_bf16 v[78:81], v[186:189], v[210:213], v[78:81]
	v_mfma_f32_16x16x32_bf16 v[74:77], v[154:157], v[232:235], v[74:77]
	v_mfma_f32_16x16x32_bf16 v[70:73], v[186:189], v[232:235], v[70:73]
	s_barrier
	s_add_i32 s18, s50, s28
	v_lshl_add_u64 v[40:41], v[220:221], 0, s[2:3]
	s_mov_b32 m0, s18
	ds_read_b128 v[190:193], v185 offset:49152
	ds_read_b128 v[194:197], v185 offset:50176
	ds_read_b128 v[198:201], v185 offset:51200
	ds_read_b128 v[202:205], v185 offset:52224
	ds_read_b128 v[206:209], v185 offset:53248
	ds_read_b128 v[210:213], v185 offset:54272
	ds_read_b128 v[214:217], v185 offset:55296
	ds_read_b128 v[232:235], v185 offset:56320
	global_load_lds_dwordx4 v[40:41], off
	s_add_i32 m0, s18, 0x2000
	s_add_u32 s18, s22, 0x180080
	v_lshl_add_u64 v[40:41], v[236:237], 0, s[2:3]
	s_addc_u32 s19, s23, 0
	s_add_i32 s22, s51, s28
	global_load_lds_dwordx4 v[40:41], off
	v_lshl_add_u64 v[40:41], s[18:19], 0, v[174:175]
	s_mov_b32 m0, s22
	s_nop 0
	global_load_lds_dwordx4 v[40:41], off
	v_lshl_add_u64 v[40:41], s[18:19], 0, v[162:163]
	s_add_i32 m0, s22, 0x2000
	s_nop 0
	global_load_lds_dwordx4 v[40:41], off
	v_lshl_add_u64 v[40:41], v[238:239], 0, s[2:3]
	s_mov_b32 m0, s42
	s_nop 0
	global_load_lds_dwordx4 v[40:41], off
	v_lshl_add_u64 v[40:41], v[240:241], 0, s[2:3]
	s_mov_b32 m0, s43
	s_nop 0
	global_load_lds_dwordx4 v[40:41], off
	s_waitcnt vmcnt(8)
	s_waitcnt lgkmcnt(0)
	s_barrier
	s_waitcnt lgkmcnt(0)
	v_mfma_f32_16x16x32_bf16 v[66:69], v[134:137], v[190:193], v[66:69]
	v_mfma_f32_16x16x32_bf16 v[62:65], v[142:145], v[190:193], v[62:65]
	v_mfma_f32_16x16x32_bf16 v[58:61], v[134:137], v[198:201], v[58:61]
	v_mfma_f32_16x16x32_bf16 v[54:57], v[142:145], v[198:201], v[54:57]
	v_mfma_f32_16x16x32_bf16 v[50:53], v[134:137], v[206:209], v[50:53]
	v_mfma_f32_16x16x32_bf16 v[46:49], v[142:145], v[206:209], v[46:49]
	v_mfma_f32_16x16x32_bf16 v[40:43], v[134:137], v[214:217], v[42:45]
	v_mfma_f32_16x16x32_bf16 v[36:39], v[142:145], v[214:217], v[36:39]
	v_mfma_f32_16x16x32_bf16 v[66:69], v[138:141], v[194:197], v[66:69]
	v_mfma_f32_16x16x32_bf16 v[62:65], v[146:149], v[194:197], v[62:65]
	v_mfma_f32_16x16x32_bf16 v[58:61], v[138:141], v[202:205], v[58:61]
	v_mfma_f32_16x16x32_bf16 v[54:57], v[146:149], v[202:205], v[54:57]
	v_mfma_f32_16x16x32_bf16 v[50:53], v[138:141], v[210:213], v[50:53]
	v_mfma_f32_16x16x32_bf16 v[46:49], v[146:149], v[210:213], v[46:49]
	v_mfma_f32_16x16x32_bf16 v[42:45], v[138:141], v[232:235], v[40:43]
	v_mfma_f32_16x16x32_bf16 v[38:41], v[146:149], v[232:235], v[36:39]
	v_mfma_f32_16x16x32_bf16 v[30:33], v[150:153], v[190:193], v[30:33]
	v_mfma_f32_16x16x32_bf16 v[26:29], v[158:161], v[190:193], v[26:29]
	v_mfma_f32_16x16x32_bf16 v[22:25], v[150:153], v[198:201], v[22:25]
	v_mfma_f32_16x16x32_bf16 v[18:21], v[158:161], v[198:201], v[18:21]
	v_mfma_f32_16x16x32_bf16 v[14:17], v[150:153], v[206:209], v[14:17]
	v_mfma_f32_16x16x32_bf16 v[10:13], v[158:161], v[206:209], v[10:13]
	v_mfma_f32_16x16x32_bf16 v[6:9], v[150:153], v[214:217], v[6:9]
	v_mfma_f32_16x16x32_bf16 v[2:5], v[158:161], v[214:217], v[2:5]
	v_mfma_f32_16x16x32_bf16 v[30:33], v[154:157], v[194:197], v[30:33]
	v_mfma_f32_16x16x32_bf16 v[26:29], v[186:189], v[194:197], v[26:29]
	v_mfma_f32_16x16x32_bf16 v[22:25], v[154:157], v[202:205], v[22:25]
	v_mfma_f32_16x16x32_bf16 v[18:21], v[186:189], v[202:205], v[18:21]
	v_mfma_f32_16x16x32_bf16 v[14:17], v[154:157], v[210:213], v[14:17]
	v_mfma_f32_16x16x32_bf16 v[10:13], v[186:189], v[210:213], v[10:13]
	v_mfma_f32_16x16x32_bf16 v[6:9], v[154:157], v[232:235], v[6:9]
	v_mfma_f32_16x16x32_bf16 v[2:5], v[186:189], v[232:235], v[2:5]
	s_barrier
	s_add_i32 s41, s41, 2
	s_add_u32 s13, s13, 0x100
	s_addc_u32 s40, s40, 0
	s_cmp_gt_u32 s41, 29
	s_mov_b64 s[18:19], s[20:21]
	s_cbranch_scc0 .LBB0_1624
	s_and_b64 vcc, exec, s[10:11]
	s_cbranch_vccz .LBB0_1627
	s_barrier

.LBB0_1732:
	s_add_u32 s20, s18, 0xfff00080
	s_addc_u32 s21, s19, -1
	s_add_i32 s47, 0, 0x10000
	s_cmp_eq_u32 s46, 60
	s_cselect_b32 s23, s13, s21
	s_cselect_b32 s22, s42, s20
	v_add_u32_e32 v1, s47, v144
	s_cselect_b32 s21, s11, s45
	s_cselect_b32 s20, s43, s44
	s_add_i32 s50, 0, 0x14000
	ds_read_b128 v[148:151], v1
	ds_read_b128 v[152:155], v1 offset:1024
	ds_read_b128 v[156:159], v1 offset:2048
	ds_read_b128 v[160:163], v1 offset:3072
	v_add_u32_e32 v1, s50, v144
	ds_read_b128 v[172:175], v1
	ds_read_b128 v[176:179], v1 offset:1024
	ds_read_b128 v[180:183], v1 offset:2048
	ds_read_b128 v[184:187], v1 offset:3072
	v_lshl_add_u64 v[216:217], s[18:19], 0, v[142:143]
	s_add_i32 m0, s29, 0xc000
	ds_read_b128 v[188:191], v146
	ds_read_b128 v[192:195], v146 offset:1024
	ds_read_b128 v[196:199], v146 offset:2048
	ds_read_b128 v[200:203], v146 offset:3072
	ds_read_b128 v[204:207], v146 offset:4096
	ds_read_b128 v[208:211], v146 offset:5120
	ds_read_b128 v[212:215], v146 offset:6144
	ds_read_b128 v[232:235], v146 offset:7168
	global_load_lds_dwordx4 v[216:217], off
	v_lshl_add_u64 v[216:217], s[18:19], 0, v[140:141]
	s_add_i32 m0, s29, 0xe000
	s_nop 0
	global_load_lds_dwordx4 v[216:217], off
	s_waitcnt vmcnt(8)
	s_waitcnt lgkmcnt(0)
	s_barrier
	s_waitcnt lgkmcnt(0)
	v_mfma_f32_16x16x32_bf16 v[128:131], v[148:151], v[188:191], v[128:131]
	v_mfma_f32_16x16x32_bf16 v[124:127], v[156:159], v[188:191], v[124:127]
	v_mfma_f32_16x16x32_bf16 v[120:123], v[148:151], v[196:199], v[120:123]
	v_mfma_f32_16x16x32_bf16 v[116:119], v[156:159], v[196:199], v[116:119]
	v_mfma_f32_16x16x32_bf16 v[104:107], v[148:151], v[204:207], v[104:107]
	v_mfma_f32_16x16x32_bf16 v[100:103], v[156:159], v[204:207], v[100:103]
	v_mfma_f32_16x16x32_bf16 v[88:91], v[148:151], v[212:215], v[88:91]
	v_mfma_f32_16x16x32_bf16 v[84:87], v[156:159], v[212:215], v[84:87]
	v_mfma_f32_16x16x32_bf16 v[128:131], v[152:155], v[192:195], v[128:131]
	v_mfma_f32_16x16x32_bf16 v[124:127], v[160:163], v[192:195], v[124:127]
	v_mfma_f32_16x16x32_bf16 v[120:123], v[152:155], v[200:203], v[120:123]
	v_mfma_f32_16x16x32_bf16 v[116:119], v[160:163], v[200:203], v[116:119]
	v_mfma_f32_16x16x32_bf16 v[104:107], v[152:155], v[208:211], v[104:107]
	v_mfma_f32_16x16x32_bf16 v[100:103], v[160:163], v[208:211], v[100:103]
	v_mfma_f32_16x16x32_bf16 v[88:91], v[152:155], v[232:235], v[88:91]
	v_mfma_f32_16x16x32_bf16 v[84:87], v[160:163], v[232:235], v[84:87]
	v_mfma_f32_16x16x32_bf16 v[112:115], v[172:175], v[188:191], v[112:115]
	v_mfma_f32_16x16x32_bf16 v[108:111], v[180:183], v[188:191], v[108:111]
	v_mfma_f32_16x16x32_bf16 v[96:99], v[172:175], v[196:199], v[96:99]
	v_mfma_f32_16x16x32_bf16 v[92:95], v[180:183], v[196:199], v[92:95]
	v_mfma_f32_16x16x32_bf16 v[80:83], v[172:175], v[204:207], v[80:83]
	v_mfma_f32_16x16x32_bf16 v[76:79], v[180:183], v[204:207], v[76:79]
	v_mfma_f32_16x16x32_bf16 v[72:75], v[172:175], v[212:215], v[72:75]
	v_mfma_f32_16x16x32_bf16 v[68:71], v[180:183], v[212:215], v[68:71]
	v_mfma_f32_16x16x32_bf16 v[112:115], v[176:179], v[192:195], v[112:115]
	v_mfma_f32_16x16x32_bf16 v[108:111], v[184:187], v[192:195], v[108:111]
	v_mfma_f32_16x16x32_bf16 v[96:99], v[176:179], v[200:203], v[96:99]
	v_mfma_f32_16x16x32_bf16 v[92:95], v[184:187], v[200:203], v[92:95]
	v_mfma_f32_16x16x32_bf16 v[80:83], v[176:179], v[208:211], v[80:83]
	v_mfma_f32_16x16x32_bf16 v[76:79], v[184:187], v[208:211], v[76:79]
	v_mfma_f32_16x16x32_bf16 v[72:75], v[176:179], v[232:235], v[72:75]
	v_mfma_f32_16x16x32_bf16 v[68:71], v[184:187], v[232:235], v[68:71]
	s_barrier
	s_add_i32 s47, s47, s26
	v_lshl_add_u64 v[216:217], s[20:21], 0, v[136:137]
	s_mov_b32 m0, s47
	ds_read_b128 v[188:191], v146 offset:16384
	ds_read_b128 v[192:195], v146 offset:17408
	ds_read_b128 v[196:199], v146 offset:18432
	ds_read_b128 v[200:203], v146 offset:19456
	ds_read_b128 v[204:207], v146 offset:20480
	ds_read_b128 v[208:211], v146 offset:21504
	ds_read_b128 v[212:215], v146 offset:22528
	ds_read_b128 v[232:235], v146 offset:23552
	global_load_lds_dwordx4 v[216:217], off
	s_add_i32 m0, s47, 0x2000
	s_add_u32 s48, s20, 0x100000
	v_lshl_add_u64 v[220:221], s[20:21], 0, v[132:133]
	s_addc_u32 s49, s21, 0
	s_add_i32 s47, s50, s26
	global_load_lds_dwordx4 v[220:221], off
	v_lshl_add_u64 v[236:237], s[48:49], 0, v[136:137]
	s_mov_b32 m0, s47
	v_lshl_add_u64 v[238:239], s[22:23], 0, v[134:135]
	global_load_lds_dwordx4 v[236:237], off
	v_lshl_add_u64 v[236:237], s[48:49], 0, v[132:133]
	s_add_i32 m0, s47, 0x2000
	s_nop 0
	global_load_lds_dwordx4 v[236:237], off
	v_lshl_add_u64 v[236:237], s[22:23], 0, v[138:139]
	s_mov_b32 m0, s29
	s_nop 0
	global_load_lds_dwordx4 v[236:237], off
	s_mov_b32 m0, s30
	s_nop 0
	global_load_lds_dwordx4 v[238:239], off
	s_waitcnt vmcnt(8)
	s_waitcnt lgkmcnt(0)
	s_barrier
	s_waitcnt lgkmcnt(0)
	v_mfma_f32_16x16x32_bf16 v[60:63], v[148:151], v[188:191], v[60:63]
	v_mfma_f32_16x16x32_bf16 v[56:59], v[156:159], v[188:191], v[56:59]
	v_mfma_f32_16x16x32_bf16 v[44:47], v[148:151], v[196:199], v[44:47]
	v_mfma_f32_16x16x32_bf16 v[40:43], v[156:159], v[196:199], v[40:43]
	v_mfma_f32_16x16x32_bf16 v[26:29], v[148:151], v[204:207], v[26:29]
	v_mfma_f32_16x16x32_bf16 v[22:25], v[156:159], v[204:207], v[22:25]
	v_mfma_f32_16x16x32_bf16 v[10:13], v[148:151], v[212:215], v[10:13]
	v_mfma_f32_16x16x32_bf16 v[6:9], v[156:159], v[212:215], v[6:9]
	v_mfma_f32_16x16x32_bf16 v[60:63], v[152:155], v[192:195], v[60:63]
	v_mfma_f32_16x16x32_bf16 v[56:59], v[160:163], v[192:195], v[56:59]
	v_mfma_f32_16x16x32_bf16 v[44:47], v[152:155], v[200:203], v[44:47]
	v_mfma_f32_16x16x32_bf16 v[40:43], v[160:163], v[200:203], v[40:43]
	v_mfma_f32_16x16x32_bf16 v[26:29], v[152:155], v[208:211], v[26:29]
	v_mfma_f32_16x16x32_bf16 v[22:25], v[160:163], v[208:211], v[22:25]
	v_mfma_f32_16x16x32_bf16 v[10:13], v[152:155], v[232:235], v[10:13]
	v_mfma_f32_16x16x32_bf16 v[6:9], v[160:163], v[232:235], v[6:9]
	v_mfma_f32_16x16x32_bf16 v[36:39], v[172:175], v[188:191], v[36:39]
	v_mfma_f32_16x16x32_bf16 v[30:33], v[180:183], v[188:191], v[30:33]
	v_mfma_f32_16x16x32_bf16 v[18:21], v[172:175], v[196:199], v[18:21]
	v_mfma_f32_16x16x32_bf16 v[14:17], v[180:183], v[196:199], v[14:17]
	v_mfma_f32_16x16x32_bf16 v[2:5], v[172:175], v[204:207], v[2:5]
	v_mfma_f32_16x16x32_bf16 v[64:67], v[180:183], v[204:207], v[64:67]
	v_mfma_f32_16x16x32_bf16 v[48:51], v[172:175], v[212:215], v[48:51]
	v_mfma_f32_16x16x32_bf16 v[52:55], v[180:183], v[212:215], v[52:55]
	v_mfma_f32_16x16x32_bf16 v[36:39], v[176:179], v[192:195], v[36:39]
	v_mfma_f32_16x16x32_bf16 v[30:33], v[184:187], v[192:195], v[30:33]
	v_mfma_f32_16x16x32_bf16 v[18:21], v[176:179], v[200:203], v[18:21]
	v_mfma_f32_16x16x32_bf16 v[14:17], v[184:187], v[200:203], v[14:17]
	v_mfma_f32_16x16x32_bf16 v[2:5], v[176:179], v[208:211], v[2:5]
	v_mfma_f32_16x16x32_bf16 v[64:67], v[184:187], v[208:211], v[64:67]
	v_mfma_f32_16x16x32_bf16 v[48:51], v[176:179], v[232:235], v[48:51]
	v_mfma_f32_16x16x32_bf16 v[52:55], v[184:187], v[232:235], v[52:55]
	s_barrier
	s_add_i32 s47, 0, 0x18000
	v_add_u32_e32 v1, s47, v144
	s_add_i32 s48, 0, 0x1c000
	ds_read_b128 v[148:151], v1
	ds_read_b128 v[152:155], v1 offset:1024
	ds_read_b128 v[156:159], v1 offset:2048
	ds_read_b128 v[160:163], v1 offset:3072
	v_add_u32_e32 v1, s48, v144
	ds_read_b128 v[172:175], v1
	ds_read_b128 v[176:179], v1 offset:1024
	ds_read_b128 v[180:183], v1 offset:2048
	ds_read_b128 v[184:187], v1 offset:3072
	s_add_u32 s22, s22, 0x100000
	s_addc_u32 s23, s23, 0
	s_mov_b32 m0, s31
	v_lshl_add_u64 v[240:241], s[22:23], 0, v[138:139]
	ds_read_b128 v[188:191], v146 offset:32768
	ds_read_b128 v[192:195], v146 offset:33792
	ds_read_b128 v[196:199], v146 offset:34816
	ds_read_b128 v[200:203], v146 offset:35840
	ds_read_b128 v[204:207], v146 offset:36864
	ds_read_b128 v[208:211], v146 offset:37888
	ds_read_b128 v[212:215], v146 offset:38912
	ds_read_b128 v[232:235], v146 offset:39936
	global_load_lds_dwordx4 v[240:241], off
	v_lshl_add_u64 v[240:241], s[22:23], 0, v[134:135]
	s_mov_b32 m0, s34
	s_nop 0
	global_load_lds_dwordx4 v[240:241], off
	s_waitcnt vmcnt(8)
	s_waitcnt lgkmcnt(0)
	s_barrier
	s_waitcnt lgkmcnt(0)
	v_mfma_f32_16x16x32_bf16 v[128:131], v[148:151], v[188:191], v[128:131]
	v_mfma_f32_16x16x32_bf16 v[124:127], v[156:159], v[188:191], v[124:127]
	v_mfma_f32_16x16x32_bf16 v[120:123], v[148:151], v[196:199], v[120:123]
	v_mfma_f32_16x16x32_bf16 v[116:119], v[156:159], v[196:199], v[116:119]
	v_mfma_f32_16x16x32_bf16 v[104:107], v[148:151], v[204:207], v[104:107]
	v_mfma_f32_16x16x32_bf16 v[100:103], v[156:159], v[204:207], v[100:103]
	v_mfma_f32_16x16x32_bf16 v[88:91], v[148:151], v[212:215], v[88:91]
	v_mfma_f32_16x16x32_bf16 v[84:87], v[156:159], v[212:215], v[84:87]
	v_mfma_f32_16x16x32_bf16 v[128:131], v[152:155], v[192:195], v[128:131]
	v_mfma_f32_16x16x32_bf16 v[124:127], v[160:163], v[192:195], v[124:127]
	v_mfma_f32_16x16x32_bf16 v[120:123], v[152:155], v[200:203], v[120:123]
	v_mfma_f32_16x16x32_bf16 v[116:119], v[160:163], v[200:203], v[116:119]
	v_mfma_f32_16x16x32_bf16 v[104:107], v[152:155], v[208:211], v[104:107]
	v_mfma_f32_16x16x32_bf16 v[100:103], v[160:163], v[208:211], v[100:103]
	v_mfma_f32_16x16x32_bf16 v[88:91], v[152:155], v[232:235], v[88:91]
	v_mfma_f32_16x16x32_bf16 v[84:87], v[160:163], v[232:235], v[84:87]
	v_mfma_f32_16x16x32_bf16 v[112:115], v[172:175], v[188:191], v[112:115]
	v_mfma_f32_16x16x32_bf16 v[108:111], v[180:183], v[188:191], v[108:111]
	v_mfma_f32_16x16x32_bf16 v[96:99], v[172:175], v[196:199], v[96:99]
	v_mfma_f32_16x16x32_bf16 v[92:95], v[180:183], v[196:199], v[92:95]
	v_mfma_f32_16x16x32_bf16 v[80:83], v[172:175], v[204:207], v[80:83]
	v_mfma_f32_16x16x32_bf16 v[76:79], v[180:183], v[204:207], v[76:79]
	v_mfma_f32_16x16x32_bf16 v[72:75], v[172:175], v[212:215], v[72:75]
	v_mfma_f32_16x16x32_bf16 v[68:71], v[180:183], v[212:215], v[68:71]
	v_mfma_f32_16x16x32_bf16 v[112:115], v[176:179], v[192:195], v[112:115]
	v_mfma_f32_16x16x32_bf16 v[108:111], v[184:187], v[192:195], v[108:111]
	v_mfma_f32_16x16x32_bf16 v[96:99], v[176:179], v[200:203], v[96:99]
	v_mfma_f32_16x16x32_bf16 v[92:95], v[184:187], v[200:203], v[92:95]
	v_mfma_f32_16x16x32_bf16 v[80:83], v[176:179], v[208:211], v[80:83]
	v_mfma_f32_16x16x32_bf16 v[76:79], v[184:187], v[208:211], v[76:79]
	v_mfma_f32_16x16x32_bf16 v[72:75], v[176:179], v[232:235], v[72:75]
	v_mfma_f32_16x16x32_bf16 v[68:71], v[184:187], v[232:235], v[68:71]
	s_barrier
	s_add_i32 s22, s47, s26
	v_lshl_add_u64 v[216:217], v[216:217], 0, s[2:3]
	s_mov_b32 m0, s22
	ds_read_b128 v[188:191], v146 offset:49152
	ds_read_b128 v[192:195], v146 offset:50176
	ds_read_b128 v[196:199], v146 offset:51200
	ds_read_b128 v[200:203], v146 offset:52224
	ds_read_b128 v[204:207], v146 offset:53248
	ds_read_b128 v[208:211], v146 offset:54272
	ds_read_b128 v[212:215], v146 offset:55296
	ds_read_b128 v[232:235], v146 offset:56320
	global_load_lds_dwordx4 v[216:217], off
	s_add_i32 m0, s22, 0x2000
	s_add_u32 s20, s20, 0x100080
	v_lshl_add_u64 v[216:217], v[220:221], 0, s[2:3]
	s_addc_u32 s21, s21, 0
	s_add_i32 s22, s48, s26
	global_load_lds_dwordx4 v[216:217], off
	v_lshl_add_u64 v[216:217], s[20:21], 0, v[136:137]
	s_mov_b32 m0, s22
	s_nop 0
	global_load_lds_dwordx4 v[216:217], off
	v_lshl_add_u64 v[216:217], s[20:21], 0, v[132:133]
	s_add_i32 m0, s22, 0x2000
	s_nop 0
	global_load_lds_dwordx4 v[216:217], off
	v_lshl_add_u64 v[216:217], v[236:237], 0, s[2:3]
	s_mov_b32 m0, s35
	s_nop 0
	global_load_lds_dwordx4 v[216:217], off
	v_lshl_add_u64 v[216:217], v[238:239], 0, s[2:3]
	s_mov_b32 m0, s38
	s_nop 0
	global_load_lds_dwordx4 v[216:217], off
	s_waitcnt vmcnt(8)
	s_waitcnt lgkmcnt(0)
	s_barrier
	s_waitcnt lgkmcnt(0)
	v_mfma_f32_16x16x32_bf16 v[60:63], v[148:151], v[188:191], v[60:63]
	v_mfma_f32_16x16x32_bf16 v[56:59], v[156:159], v[188:191], v[56:59]
	v_mfma_f32_16x16x32_bf16 v[44:47], v[148:151], v[196:199], v[44:47]
	v_mfma_f32_16x16x32_bf16 v[40:43], v[156:159], v[196:199], v[40:43]
	v_mfma_f32_16x16x32_bf16 v[26:29], v[148:151], v[204:207], v[26:29]
	v_mfma_f32_16x16x32_bf16 v[22:25], v[156:159], v[204:207], v[22:25]
	v_mfma_f32_16x16x32_bf16 v[10:13], v[148:151], v[212:215], v[10:13]
	v_mfma_f32_16x16x32_bf16 v[6:9], v[156:159], v[212:215], v[6:9]
	v_mfma_f32_16x16x32_bf16 v[60:63], v[152:155], v[192:195], v[60:63]
	v_mfma_f32_16x16x32_bf16 v[56:59], v[160:163], v[192:195], v[56:59]
	v_mfma_f32_16x16x32_bf16 v[44:47], v[152:155], v[200:203], v[44:47]
	v_mfma_f32_16x16x32_bf16 v[40:43], v[160:163], v[200:203], v[40:43]
	v_mfma_f32_16x16x32_bf16 v[26:29], v[152:155], v[208:211], v[26:29]
	v_mfma_f32_16x16x32_bf16 v[22:25], v[160:163], v[208:211], v[22:25]
	v_mfma_f32_16x16x32_bf16 v[10:13], v[152:155], v[232:235], v[10:13]
	v_mfma_f32_16x16x32_bf16 v[6:9], v[160:163], v[232:235], v[6:9]
	v_mfma_f32_16x16x32_bf16 v[36:39], v[172:175], v[188:191], v[36:39]
	v_mfma_f32_16x16x32_bf16 v[30:33], v[180:183], v[188:191], v[30:33]
	v_mfma_f32_16x16x32_bf16 v[18:21], v[172:175], v[196:199], v[18:21]
	v_mfma_f32_16x16x32_bf16 v[14:17], v[180:183], v[196:199], v[14:17]
	v_mfma_f32_16x16x32_bf16 v[2:5], v[172:175], v[204:207], v[2:5]
	v_mfma_f32_16x16x32_bf16 v[64:67], v[180:183], v[204:207], v[64:67]
	v_mfma_f32_16x16x32_bf16 v[48:51], v[172:175], v[212:215], v[48:51]
	v_mfma_f32_16x16x32_bf16 v[52:55], v[180:183], v[212:215], v[52:55]
	v_mfma_f32_16x16x32_bf16 v[36:39], v[176:179], v[192:195], v[36:39]
	v_mfma_f32_16x16x32_bf16 v[30:33], v[184:187], v[192:195], v[30:33]
	v_mfma_f32_16x16x32_bf16 v[18:21], v[176:179], v[200:203], v[18:21]
	v_mfma_f32_16x16x32_bf16 v[14:17], v[184:187], v[200:203], v[14:17]
	v_mfma_f32_16x16x32_bf16 v[2:5], v[176:179], v[208:211], v[2:5]
	v_mfma_f32_16x16x32_bf16 v[64:67], v[184:187], v[208:211], v[64:67]
	v_mfma_f32_16x16x32_bf16 v[48:51], v[176:179], v[232:235], v[48:51]
	v_mfma_f32_16x16x32_bf16 v[52:55], v[184:187], v[232:235], v[52:55]
	s_barrier
	s_add_i32 s46, s46, 2
	s_add_u32 s44, s44, 0x100
	s_addc_u32 s45, s45, 0
	s_add_u32 s18, s18, 0x100
	s_addc_u32 s19, s19, 0
	s_cmp_gt_u32 s46, 61
	s_cbranch_scc0 .LBB0_1732
	s_and_b64 vcc, exec, s[8:9]
	s_cbranch_vccz .LBB0_1735
	s_barrier
